# unit-transition grace (As[1][1] pre-staged, 3 satisfied waits skipped) in P1, P3, P7 on top of nt stores, HGRN wait fix, attention tr hoist
# speedup vs baseline: 1.0077x; 1.0023x over previous
;     __host__ __device__ bool next(int i, Unit& u) const {
;         const long L = (long)i * G + c; if (L >= nwg) return false;
;         int wgid = (int)L; { const int q = nwg / NXCD, r = nwg % NXCD, xcd = wgid % NXCD, off = wgid / NXCD; wgid = (xcd < r ? xcd * (q + 1) : r * (q + 1) + (xcd - r) * q) + off; }
;         const int nig = WGM * nN, gid = wgid / nig, fm = gid * WGM, gsz = (nM - fm) < WGM ? (nM - fm) : WGM;
;         u.pm = fm + ((wgid % nig) % gsz); u.pn = (wgid % nig) / gsz; return true;
;     }
; template <class Epi, class Sched, bool ALIGN_EPI = false, bool SP2 = false>
; __device__ __forceinline__ void gemm_phase(PG8_LAS unsigned char* lds, const Gemm g, const Sched& S, const Epi& E) {
;     ...
;     Unit cur, nxt; int ui = 0;
;     if (!S.next(0, cur)) return;
.LBB0_358:
	s_cmp_lt_i32 s66, 4
	s_cselect_b64 s[0:1], -1, 0
	s_add_u32 s76, s64, 0x18f00000
	s_waitcnt lgkmcnt(0)
	s_addc_u32 s50, s65, 0
	s_and_b64 s[8:9], s[0:1], s[2:3]
	s_andn2_b64 vcc, exec, s[8:9]
	s_cbranch_vccnz .LBB0_450
	s_mov_b32 s100, 0
	s_cmpk_lt_i32 s77, 0xb00
	s_cselect_b64 s[2:3], -1, 0
	s_cmpk_gt_i32 s77, 0xaff
	v_readfirstlane_b32 s10, v220
	s_cbranch_scc1 .LBB0_361
	s_ashr_i32 s0, s77, 31
	s_lshr_b32 s0, s0, 29
	s_add_i32 s0, s77, s0
	s_ashr_i32 s1, s0, 3
	s_and_b32 s0, s0, -8
	s_sub_i32 s0, s77, s0
	s_cmp_lt_i32 s0, 0
	s_movk_i32 s4, 0x161
	s_cselect_b32 s4, s4, 0x160
	s_mul_i32 s0, s0, s4
	s_add_i32 s0, s0, s1
	s_mul_hi_i32 s1, s0, 0x2e8ba2e9
	s_lshr_b32 s4, s1, 31
	s_ashr_i32 s1, s1, 5
	s_add_i32 s1, s1, s4
	s_lshl_b32 s4, s1, 2
	s_mulk_i32 s1, 0xb0
	s_sub_i32 s0, s0, s1
	s_sext_i32_i16 s1, s0
	s_bfe_u32 s1, s1, 0x2001d
	s_add_i32 s1, s0, s1
	s_sext_i32_i16 s5, s1
	s_and_b32 s1, s1, 0xfffc
	s_sub_i32 s0, s0, s1
	s_sext_i32_i16 s0, s0
	s_add_i32 s40, s4, s0
	s_ashr_i32 s36, s5, 2

; #define PG8_STAGE(bufoff, gbase, voff) do { _Pragma("unroll") for (int _i = 0; _i < 2; ++_i) \
;         __builtin_amdgcn_global_load_lds((const unsigned*)((const char*)(gbase) + (voff)[_i]), (PG8_LAS unsigned*)(lds + (bufoff) + ldsw + _i * 8192), 16, 0, 0); } while (0)
; #define PG8_LDA(dst, b, h) do { _Pragma("unroll") for (int m = 0; m < 4; ++m) _Pragma("unroll") for (int k = 0; k < 2; ++k) dst[m][k] = *(const PG8_LAS bf16x8*)(lds + PG8_SA(b, h) + aoff + m * 2048 + k * 1024); } while (0)
; #define PG8_LDB(dst, b, h) do { _Pragma("unroll") for (int n = 0; n < 2; ++n) _Pragma("unroll") for (int k = 0; k < 2; ++k) dst[n][k] = *(const PG8_LAS bf16x8*)(lds + PG8_SB(b, h) + boff + n * 2048 + k * 1024); } while (0)
; #define PG8_MMA(ai, bj, At, Bt) do { __builtin_amdgcn_s_setprio(1); _Pragma("unroll") for (int m = 0; m < 4; ++m) _Pragma("unroll") for (int n = 0; n < 2; ++n) _Pragma("unroll") for (int k = 0; k < 2; ++k) \
;         acc[ai][bj][m][n] = __builtin_amdgcn_mfma_f32_16x16x32_bf16(Bt[n][k], At[m][k], acc[ai][bj][m][n], 0, 0, 0); __builtin_amdgcn_s_setprio(0); } while (0)
; #define PG8_WAIT_V(n) asm volatile("s_waitcnt vmcnt(" #n ")" ::: "memory")
; #define PG8_WAIT_L(n) asm volatile("s_waitcnt lgkmcnt(" #n ")" ::: "memory")
; #define PG8_BAR __builtin_amdgcn_s_barrier()
; #define PG8_SCHED __builtin_amdgcn_sched_barrier(0)
; template <class Epi, class Sched, bool ALIGN_EPI = false, bool SP2 = false>
; __device__ __forceinline__ void gemm_phase(PG8_LAS unsigned char* lds, const Gemm g, const Sched& S, const Epi& E) {
;     ...
;             PG8_LDB(B0, 0, 0); PG8_LDB(B1, 0, 1); PG8_SCHED; PG8_LDA(At, 0, 0); PG8_STAGE(PG8_SA(1, 1), a1 + hstep, voffA);
;             PG8_WAIT_V(8); PG8_WAIT_L(0); PG8_BAR; PG8_MMA(0, 0, At, B0); PG8_MMA(0, 1, At, B1); PG8_BAR; PG8_SCHED;
;             PG8_LDA(At, 0, 1); PG8_STAGE(PG8_SB(0, 0), b2, voffB); PG8_STAGE(PG8_SB(0, 1), b2 + hstep, voffB); PG8_STAGE(PG8_SA(0, 0), a2, voffA);
;             PG8_WAIT_V(8); PG8_WAIT_L(0); PG8_BAR; PG8_MMA(1, 0, At, B0); PG8_MMA(1, 1, At, B1); PG8_BAR; PG8_SCHED;
.LBB0_370:
	ds_read_b128 v[128:131], v173
	ds_read_b128 v[132:135], v173 offset:1024
	ds_read_b128 v[156:159], v173 offset:2048
	ds_read_b128 v[160:163], v173 offset:3072
	ds_read_b128 v[164:167], v174
	ds_read_b128 v[178:181], v174 offset:1024
	ds_read_b128 v[182:185], v174 offset:2048
	ds_read_b128 v[186:189], v174 offset:3072
	s_add_u32 s6, s4, 0xfff80080
	s_addc_u32 s7, s5, -1
	s_cmp_eq_u32 s47, 28
	s_cselect_b32 s43, s10, s7
	s_cselect_b32 s42, s29, s6
	s_cselect_b32 s7, s27, s46
	s_cselect_b32 s6, s44, s45
	v_lshl_add_u64 v[168:169], s[4:5], 0, v[146:147]
	s_add_i32 m0, s1, 0xc000
	ds_read_b128 v[190:193], v175
	ds_read_b128 v[194:197], v175 offset:1024
	ds_read_b128 v[198:201], v175 offset:2048
	ds_read_b128 v[206:209], v175 offset:3072
	ds_read_b128 v[210:213], v175 offset:4096
	ds_read_b128 v[214:217], v175 offset:5120
	ds_read_b128 v[222:225], v175 offset:6144
	ds_read_b128 v[226:229], v175 offset:7168
	s_cmp_lg_u32 s100, 0
	s_cbranch_scc1 .Lgr_p3_0
	global_load_lds_dwordx4 v[168:169], off
	v_lshl_add_u64 v[168:169], s[4:5], 0, v[148:149]
	s_add_i32 m0, s1, 0xe000
	s_nop 0
	global_load_lds_dwordx4 v[168:169], off
	s_waitcnt vmcnt(8)
.Lgr_p3_0:
	s_waitcnt lgkmcnt(0)
	s_barrier
	s_setprio 1
	s_waitcnt lgkmcnt(0)
	v_mfma_f32_16x16x32_bf16 v[124:127], v[128:131], v[190:193], v[124:127]
	v_mfma_f32_16x16x32_bf16 v[120:123], v[156:159], v[190:193], v[120:123]
	v_mfma_f32_16x16x32_bf16 v[108:111], v[128:131], v[198:201], v[108:111]
	v_mfma_f32_16x16x32_bf16 v[104:107], v[156:159], v[198:201], v[104:107]
	v_mfma_f32_16x16x32_bf16 v[92:95], v[128:131], v[210:213], v[92:95]
	v_mfma_f32_16x16x32_bf16 v[88:91], v[156:159], v[210:213], v[88:91]
	v_mfma_f32_16x16x32_bf16 v[76:79], v[128:131], v[222:225], v[76:79]
	v_mfma_f32_16x16x32_bf16 v[72:75], v[156:159], v[222:225], v[72:75]
	v_mfma_f32_16x16x32_bf16 v[124:127], v[132:135], v[194:197], v[124:127]
	v_mfma_f32_16x16x32_bf16 v[120:123], v[160:163], v[194:197], v[120:123]
	v_mfma_f32_16x16x32_bf16 v[108:111], v[132:135], v[206:209], v[108:111]
	v_mfma_f32_16x16x32_bf16 v[104:107], v[160:163], v[206:209], v[104:107]
	v_mfma_f32_16x16x32_bf16 v[92:95], v[132:135], v[214:217], v[92:95]
	v_mfma_f32_16x16x32_bf16 v[88:91], v[160:163], v[214:217], v[88:91]
	v_mfma_f32_16x16x32_bf16 v[76:79], v[132:135], v[226:229], v[76:79]
	v_mfma_f32_16x16x32_bf16 v[72:75], v[160:163], v[226:229], v[72:75]
	s_setprio 0
	s_setprio 1
	v_mfma_f32_16x16x32_bf16 v[116:119], v[164:167], v[190:193], v[116:119]
	v_mfma_f32_16x16x32_bf16 v[112:115], v[182:185], v[190:193], v[112:115]
	v_mfma_f32_16x16x32_bf16 v[100:103], v[164:167], v[198:201], v[100:103]
	v_mfma_f32_16x16x32_bf16 v[96:99], v[182:185], v[198:201], v[96:99]
	v_mfma_f32_16x16x32_bf16 v[84:87], v[164:167], v[210:213], v[84:87]
	v_mfma_f32_16x16x32_bf16 v[80:83], v[182:185], v[210:213], v[80:83]
	v_mfma_f32_16x16x32_bf16 v[68:71], v[164:167], v[222:225], v[68:71]
	v_mfma_f32_16x16x32_bf16 v[64:67], v[182:185], v[222:225], v[64:67]
	v_mfma_f32_16x16x32_bf16 v[116:119], v[178:181], v[194:197], v[116:119]
	v_mfma_f32_16x16x32_bf16 v[112:115], v[186:189], v[194:197], v[112:115]
	v_mfma_f32_16x16x32_bf16 v[100:103], v[178:181], v[206:209], v[100:103]
	v_mfma_f32_16x16x32_bf16 v[96:99], v[186:189], v[206:209], v[96:99]
	v_mfma_f32_16x16x32_bf16 v[84:87], v[178:181], v[214:217], v[84:87]
	v_mfma_f32_16x16x32_bf16 v[80:83], v[186:189], v[214:217], v[80:83]
	v_mfma_f32_16x16x32_bf16 v[68:71], v[178:181], v[226:229], v[68:71]
	v_mfma_f32_16x16x32_bf16 v[64:67], v[186:189], v[226:229], v[64:67]
	s_setprio 0
	s_barrier
	s_add_i32 s69, s53, s0
	v_lshl_add_u64 v[168:169], s[6:7], 0, v[138:139]
	s_mov_b32 m0, s69
	ds_read_b128 v[190:193], v175 offset:16384
	ds_read_b128 v[194:197], v175 offset:17408
	ds_read_b128 v[198:201], v175 offset:18432
	ds_read_b128 v[206:209], v175 offset:19456
	ds_read_b128 v[210:213], v175 offset:20480
	ds_read_b128 v[214:217], v175 offset:21504
	ds_read_b128 v[222:225], v175 offset:22528
	ds_read_b128 v[226:229], v175 offset:23552
	global_load_lds_dwordx4 v[168:169], off
	s_add_i32 m0, s69, 0x2000
	s_add_u32 s70, s6, 0x80000
	v_lshl_add_u64 v[202:203], s[6:7], 0, v[142:143]
	s_addc_u32 s71, s7, 0
	s_add_i32 s69, s54, s0
	global_load_lds_dwordx4 v[202:203], off
	v_lshl_add_u64 v[218:219], s[70:71], 0, v[138:139]
	s_mov_b32 m0, s69
	v_lshl_add_u64 v[230:231], s[42:43], 0, v[140:141]
	global_load_lds_dwordx4 v[218:219], off
	v_lshl_add_u64 v[218:219], s[70:71], 0, v[142:143]
	s_add_i32 m0, s69, 0x2000
	s_nop 0
	global_load_lds_dwordx4 v[218:219], off
	v_lshl_add_u64 v[218:219], s[42:43], 0, v[136:137]
	s_mov_b32 m0, s1
	s_nop 0
	global_load_lds_dwordx4 v[218:219], off
	s_mov_b32 m0, s33
	s_nop 0
	global_load_lds_dwordx4 v[230:231], off
	s_cmp_lg_u32 s100, 0
	s_cbranch_scc1 .Lgr_p3_1
	s_waitcnt vmcnt(8)
; #define PG8_STAGE(bufoff, gbase, voff) do { _Pragma("unroll") for (int _i = 0; _i < 2; ++_i) \
;         __builtin_amdgcn_global_load_lds((const unsigned*)((const char*)(gbase) + (voff)[_i]), (PG8_LAS unsigned*)(lds + (bufoff) + ldsw + _i * 8192), 16, 0, 0); } while (0)
; #define PG8_LDA(dst, b, h) do { _Pragma("unroll") for (int m = 0; m < 4; ++m) _Pragma("unroll") for (int k = 0; k < 2; ++k) dst[m][k] = *(const PG8_LAS bf16x8*)(lds + PG8_SA(b, h) + aoff + m * 2048 + k * 1024); } while (0)
; #define PG8_LDB(dst, b, h) do { _Pragma("unroll") for (int n = 0; n < 2; ++n) _Pragma("unroll") for (int k = 0; k < 2; ++k) dst[n][k] = *(const PG8_LAS bf16x8*)(lds + PG8_SB(b, h) + boff + n * 2048 + k * 1024); } while (0)
; #define PG8_MMA(ai, bj, At, Bt) do { __builtin_amdgcn_s_setprio(1); _Pragma("unroll") for (int m = 0; m < 4; ++m) _Pragma("unroll") for (int n = 0; n < 2; ++n) _Pragma("unroll") for (int k = 0; k < 2; ++k) \
;         acc[ai][bj][m][n] = __builtin_amdgcn_mfma_f32_16x16x32_bf16(Bt[n][k], At[m][k], acc[ai][bj][m][n], 0, 0, 0); __builtin_amdgcn_s_setprio(0); } while (0)
; #define PG8_WAIT_V(n) asm volatile("s_waitcnt vmcnt(" #n ")" ::: "memory")
; #define PG8_WAIT_L(n) asm volatile("s_waitcnt lgkmcnt(" #n ")" ::: "memory")
; #define PG8_BAR __builtin_amdgcn_s_barrier()
; #define PG8_SCHED __builtin_amdgcn_sched_barrier(0)
; template <class Epi, class Sched, bool ALIGN_EPI = false, bool SP2 = false>
; __device__ __forceinline__ void gemm_phase(PG8_LAS unsigned char* lds, const Gemm g, const Sched& S, const Epi& E) {
;     ...
;             PG8_WAIT_V(8); PG8_WAIT_L(0); PG8_BAR; PG8_MMA(1, 0, At, B0); PG8_MMA(1, 1, At, B1); PG8_BAR; PG8_SCHED;
;             PG8_LDB(B0, 1, 0); PG8_LDB(B1, 1, 1); PG8_SCHED; PG8_LDA(At, 1, 0); PG8_STAGE(PG8_SA(0, 1), a2 + hstep, voffA);
;             PG8_WAIT_V(8); PG8_WAIT_L(0); PG8_BAR; PG8_MMA(0, 0, At, B0); PG8_MMA(0, 1, At, B1); PG8_BAR; PG8_SCHED;
.Lgr_p3_1:
	s_waitcnt lgkmcnt(0)
	s_barrier
	s_setprio 1
	s_waitcnt lgkmcnt(0)
	v_mfma_f32_16x16x32_bf16 v[60:63], v[128:131], v[190:193], v[60:63]
	v_mfma_f32_16x16x32_bf16 v[56:59], v[156:159], v[190:193], v[56:59]
	v_mfma_f32_16x16x32_bf16 v[44:47], v[128:131], v[198:201], v[44:47]
	v_mfma_f32_16x16x32_bf16 v[40:43], v[156:159], v[198:201], v[40:43]
	v_mfma_f32_16x16x32_bf16 v[28:31], v[128:131], v[210:213], v[28:31]
	v_mfma_f32_16x16x32_bf16 v[24:27], v[156:159], v[210:213], v[24:27]
	v_mfma_f32_16x16x32_bf16 v[12:15], v[128:131], v[222:225], v[12:15]
	v_mfma_f32_16x16x32_bf16 v[8:11], v[156:159], v[222:225], v[8:11]
	v_mfma_f32_16x16x32_bf16 v[60:63], v[132:135], v[194:197], v[60:63]
	v_mfma_f32_16x16x32_bf16 v[56:59], v[160:163], v[194:197], v[56:59]
	v_mfma_f32_16x16x32_bf16 v[44:47], v[132:135], v[206:209], v[44:47]
	v_mfma_f32_16x16x32_bf16 v[40:43], v[160:163], v[206:209], v[40:43]
	v_mfma_f32_16x16x32_bf16 v[28:31], v[132:135], v[214:217], v[28:31]
	v_mfma_f32_16x16x32_bf16 v[24:27], v[160:163], v[214:217], v[24:27]
	v_mfma_f32_16x16x32_bf16 v[12:15], v[132:135], v[226:229], v[12:15]
	v_mfma_f32_16x16x32_bf16 v[8:11], v[160:163], v[226:229], v[8:11]
	s_setprio 0
	s_setprio 1
	v_mfma_f32_16x16x32_bf16 v[52:55], v[164:167], v[190:193], v[52:55]
	v_mfma_f32_16x16x32_bf16 v[48:51], v[182:185], v[190:193], v[48:51]
	v_mfma_f32_16x16x32_bf16 v[36:39], v[164:167], v[198:201], v[36:39]
	v_mfma_f32_16x16x32_bf16 v[32:35], v[182:185], v[198:201], v[32:35]
	v_mfma_f32_16x16x32_bf16 v[20:23], v[164:167], v[210:213], v[20:23]
	v_mfma_f32_16x16x32_bf16 v[16:19], v[182:185], v[210:213], v[16:19]
	v_mfma_f32_16x16x32_bf16 v[4:7], v[164:167], v[222:225], v[4:7]
	v_mfma_f32_16x16x32_bf16 v[0:3], v[182:185], v[222:225], v[0:3]
	v_mfma_f32_16x16x32_bf16 v[52:55], v[178:181], v[194:197], v[52:55]
	v_mfma_f32_16x16x32_bf16 v[48:51], v[186:189], v[194:197], v[48:51]
	v_mfma_f32_16x16x32_bf16 v[36:39], v[178:181], v[206:209], v[36:39]
	v_mfma_f32_16x16x32_bf16 v[32:35], v[186:189], v[206:209], v[32:35]
	v_mfma_f32_16x16x32_bf16 v[20:23], v[178:181], v[214:217], v[20:23]
	v_mfma_f32_16x16x32_bf16 v[16:19], v[186:189], v[214:217], v[16:19]
	v_mfma_f32_16x16x32_bf16 v[4:7], v[178:181], v[226:229], v[4:7]
	v_mfma_f32_16x16x32_bf16 v[0:3], v[186:189], v[226:229], v[0:3]
	s_setprio 0
	s_barrier
	s_add_i32 s69, 0, 0x18000
	v_add_u32_e32 v144, s69, v171
	s_add_i32 s70, 0, 0x1c000
	ds_read_b128 v[128:131], v144
	ds_read_b128 v[132:135], v144 offset:1024
	ds_read_b128 v[156:159], v144 offset:2048
	ds_read_b128 v[160:163], v144 offset:3072
	v_add_u32_e32 v144, s70, v171
	ds_read_b128 v[164:167], v144
	ds_read_b128 v[178:181], v144 offset:1024
	ds_read_b128 v[182:185], v144 offset:2048
	ds_read_b128 v[186:189], v144 offset:3072
	s_add_u32 s42, s42, 0x80000
	s_addc_u32 s43, s43, 0
	s_mov_b32 m0, s37
	v_lshl_add_u64 v[232:233], s[42:43], 0, v[136:137]
	ds_read_b128 v[190:193], v175 offset:32768
	ds_read_b128 v[194:197], v175 offset:33792
	ds_read_b128 v[198:201], v175 offset:34816
	ds_read_b128 v[206:209], v175 offset:35840
	ds_read_b128 v[210:213], v175 offset:36864
	ds_read_b128 v[214:217], v175 offset:37888
	ds_read_b128 v[222:225], v175 offset:38912
	ds_read_b128 v[226:229], v175 offset:39936
	global_load_lds_dwordx4 v[232:233], off
	v_lshl_add_u64 v[232:233], s[42:43], 0, v[140:141]
	s_mov_b32 m0, s41
	s_nop 0
	global_load_lds_dwordx4 v[232:233], off
	s_cmp_lg_u32 s100, 0
	s_cbranch_scc1 .Lgr_p3_2
	s_waitcnt vmcnt(8)
; #define PG8_STAGE(bufoff, gbase, voff) do { _Pragma("unroll") for (int _i = 0; _i < 2; ++_i) \
;         __builtin_amdgcn_global_load_lds((const unsigned*)((const char*)(gbase) + (voff)[_i]), (PG8_LAS unsigned*)(lds + (bufoff) + ldsw + _i * 8192), 16, 0, 0); } while (0)
; #define PG8_LDA(dst, b, h) do { _Pragma("unroll") for (int m = 0; m < 4; ++m) _Pragma("unroll") for (int k = 0; k < 2; ++k) dst[m][k] = *(const PG8_LAS bf16x8*)(lds + PG8_SA(b, h) + aoff + m * 2048 + k * 1024); } while (0)
; #define PG8_MMA(ai, bj, At, Bt) do { __builtin_amdgcn_s_setprio(1); _Pragma("unroll") for (int m = 0; m < 4; ++m) _Pragma("unroll") for (int n = 0; n < 2; ++n) _Pragma("unroll") for (int k = 0; k < 2; ++k) \
;         acc[ai][bj][m][n] = __builtin_amdgcn_mfma_f32_16x16x32_bf16(Bt[n][k], At[m][k], acc[ai][bj][m][n], 0, 0, 0); __builtin_amdgcn_s_setprio(0); } while (0)
; #define PG8_WAIT_V(n) asm volatile("s_waitcnt vmcnt(" #n ")" ::: "memory")
; #define PG8_WAIT_L(n) asm volatile("s_waitcnt lgkmcnt(" #n ")" ::: "memory")
; #define PG8_BAR __builtin_amdgcn_s_barrier()
; #define PG8_SCHED __builtin_amdgcn_sched_barrier(0)
; template <class Epi, class Sched, bool ALIGN_EPI = false, bool SP2 = false>
; __device__ __forceinline__ void gemm_phase(PG8_LAS unsigned char* lds, const Gemm g, const Sched& S, const Epi& E) {
;     ...
;             PG8_WAIT_V(8); PG8_WAIT_L(0); PG8_BAR; PG8_MMA(0, 0, At, B0); PG8_MMA(0, 1, At, B1); PG8_BAR; PG8_SCHED;
;             PG8_LDA(At, 1, 1); PG8_STAGE(PG8_SB(1, 0), b3, voffB); PG8_STAGE(PG8_SB(1, 1), b3 + hstep, voffB); PG8_STAGE(PG8_SA(1, 0), a3, voffA);
;             PG8_WAIT_V(8); PG8_WAIT_L(0); PG8_BAR; PG8_MMA(1, 0, At, B0); PG8_MMA(1, 1, At, B1); PG8_BAR; PG8_SCHED;
;     ...
;         if constexpr (ALIGN_EPI) { if (wr == 0) PG8_BAR; }
;         if constexpr (!Epi::AFTER_DRAIN) { E(acc, cur, wr, wc, fr, fq); S.done(cur); }
.Lgr_p3_2:
	s_waitcnt lgkmcnt(0)
	s_barrier
	s_setprio 1
	s_waitcnt lgkmcnt(0)
	v_mfma_f32_16x16x32_bf16 v[124:127], v[128:131], v[190:193], v[124:127]
	v_mfma_f32_16x16x32_bf16 v[120:123], v[156:159], v[190:193], v[120:123]
	v_mfma_f32_16x16x32_bf16 v[108:111], v[128:131], v[198:201], v[108:111]
	v_mfma_f32_16x16x32_bf16 v[104:107], v[156:159], v[198:201], v[104:107]
	v_mfma_f32_16x16x32_bf16 v[92:95], v[128:131], v[210:213], v[92:95]
	v_mfma_f32_16x16x32_bf16 v[88:91], v[156:159], v[210:213], v[88:91]
	v_mfma_f32_16x16x32_bf16 v[76:79], v[128:131], v[222:225], v[76:79]
	v_mfma_f32_16x16x32_bf16 v[72:75], v[156:159], v[222:225], v[72:75]
	v_mfma_f32_16x16x32_bf16 v[124:127], v[132:135], v[194:197], v[124:127]
	v_mfma_f32_16x16x32_bf16 v[120:123], v[160:163], v[194:197], v[120:123]
	v_mfma_f32_16x16x32_bf16 v[108:111], v[132:135], v[206:209], v[108:111]
	v_mfma_f32_16x16x32_bf16 v[104:107], v[160:163], v[206:209], v[104:107]
	v_mfma_f32_16x16x32_bf16 v[92:95], v[132:135], v[214:217], v[92:95]
	v_mfma_f32_16x16x32_bf16 v[88:91], v[160:163], v[214:217], v[88:91]
	v_mfma_f32_16x16x32_bf16 v[76:79], v[132:135], v[226:229], v[76:79]
	v_mfma_f32_16x16x32_bf16 v[72:75], v[160:163], v[226:229], v[72:75]
	s_setprio 0
	s_setprio 1
	v_mfma_f32_16x16x32_bf16 v[116:119], v[164:167], v[190:193], v[116:119]
	v_mfma_f32_16x16x32_bf16 v[112:115], v[182:185], v[190:193], v[112:115]
	v_mfma_f32_16x16x32_bf16 v[100:103], v[164:167], v[198:201], v[100:103]
	v_mfma_f32_16x16x32_bf16 v[96:99], v[182:185], v[198:201], v[96:99]
	v_mfma_f32_16x16x32_bf16 v[84:87], v[164:167], v[210:213], v[84:87]
	v_mfma_f32_16x16x32_bf16 v[80:83], v[182:185], v[210:213], v[80:83]
	v_mfma_f32_16x16x32_bf16 v[68:71], v[164:167], v[222:225], v[68:71]
	v_mfma_f32_16x16x32_bf16 v[64:67], v[182:185], v[222:225], v[64:67]
	v_mfma_f32_16x16x32_bf16 v[116:119], v[178:181], v[194:197], v[116:119]
	v_mfma_f32_16x16x32_bf16 v[112:115], v[186:189], v[194:197], v[112:115]
	v_mfma_f32_16x16x32_bf16 v[100:103], v[178:181], v[206:209], v[100:103]
	v_mfma_f32_16x16x32_bf16 v[96:99], v[186:189], v[206:209], v[96:99]
	v_mfma_f32_16x16x32_bf16 v[84:87], v[178:181], v[214:217], v[84:87]
	v_mfma_f32_16x16x32_bf16 v[80:83], v[186:189], v[214:217], v[80:83]
	v_mfma_f32_16x16x32_bf16 v[68:71], v[178:181], v[226:229], v[68:71]
	v_mfma_f32_16x16x32_bf16 v[64:67], v[186:189], v[226:229], v[64:67]
	s_setprio 0
	s_barrier
	s_add_i32 s42, s69, s0
	v_lshl_add_u64 v[168:169], v[168:169], 0, s[16:17]
	s_mov_b32 m0, s42
	ds_read_b128 v[190:193], v175 offset:49152
	ds_read_b128 v[194:197], v175 offset:50176
	ds_read_b128 v[198:201], v175 offset:51200
	ds_read_b128 v[206:209], v175 offset:52224
	ds_read_b128 v[210:213], v175 offset:53248
	ds_read_b128 v[214:217], v175 offset:54272
	ds_read_b128 v[222:225], v175 offset:55296
	ds_read_b128 v[226:229], v175 offset:56320
	global_load_lds_dwordx4 v[168:169], off
	s_add_i32 m0, s42, 0x2000
	s_add_u32 s6, s6, 0x80080
	v_lshl_add_u64 v[168:169], v[202:203], 0, s[16:17]
	s_addc_u32 s7, s7, 0
	s_add_i32 s42, s70, s0
	global_load_lds_dwordx4 v[168:169], off
	v_lshl_add_u64 v[168:169], s[6:7], 0, v[138:139]
	s_mov_b32 m0, s42
	s_nop 0
	global_load_lds_dwordx4 v[168:169], off
	v_lshl_add_u64 v[168:169], s[6:7], 0, v[142:143]
	s_add_i32 m0, s42, 0x2000
	s_nop 0
	global_load_lds_dwordx4 v[168:169], off
	v_lshl_add_u64 v[168:169], v[218:219], 0, s[16:17]
	s_mov_b32 m0, s48
	s_nop 0
	global_load_lds_dwordx4 v[168:169], off
	v_lshl_add_u64 v[168:169], v[230:231], 0, s[16:17]
	s_mov_b32 m0, s49
	s_nop 0
	global_load_lds_dwordx4 v[168:169], off
	s_waitcnt vmcnt(8)
	s_waitcnt lgkmcnt(0)
	s_barrier
	s_setprio 1
	s_waitcnt lgkmcnt(0)
	v_mfma_f32_16x16x32_bf16 v[60:63], v[128:131], v[190:193], v[60:63]
	v_mfma_f32_16x16x32_bf16 v[56:59], v[156:159], v[190:193], v[56:59]
	v_mfma_f32_16x16x32_bf16 v[44:47], v[128:131], v[198:201], v[44:47]
	v_mfma_f32_16x16x32_bf16 v[40:43], v[156:159], v[198:201], v[40:43]
	v_mfma_f32_16x16x32_bf16 v[28:31], v[128:131], v[210:213], v[28:31]
	v_mfma_f32_16x16x32_bf16 v[24:27], v[156:159], v[210:213], v[24:27]
	v_mfma_f32_16x16x32_bf16 v[12:15], v[128:131], v[222:225], v[12:15]
	v_mfma_f32_16x16x32_bf16 v[8:11], v[156:159], v[222:225], v[8:11]
	v_mfma_f32_16x16x32_bf16 v[60:63], v[132:135], v[194:197], v[60:63]
	v_mfma_f32_16x16x32_bf16 v[56:59], v[160:163], v[194:197], v[56:59]
	v_mfma_f32_16x16x32_bf16 v[44:47], v[132:135], v[206:209], v[44:47]
	v_mfma_f32_16x16x32_bf16 v[40:43], v[160:163], v[206:209], v[40:43]
	v_mfma_f32_16x16x32_bf16 v[28:31], v[132:135], v[214:217], v[28:31]
	v_mfma_f32_16x16x32_bf16 v[24:27], v[160:163], v[214:217], v[24:27]
	v_mfma_f32_16x16x32_bf16 v[12:15], v[132:135], v[226:229], v[12:15]
	v_mfma_f32_16x16x32_bf16 v[8:11], v[160:163], v[226:229], v[8:11]
	s_setprio 0
	s_setprio 1
	v_mfma_f32_16x16x32_bf16 v[52:55], v[164:167], v[190:193], v[52:55]
	v_mfma_f32_16x16x32_bf16 v[48:51], v[182:185], v[190:193], v[48:51]
	v_mfma_f32_16x16x32_bf16 v[36:39], v[164:167], v[198:201], v[36:39]
	v_mfma_f32_16x16x32_bf16 v[32:35], v[182:185], v[198:201], v[32:35]
	v_mfma_f32_16x16x32_bf16 v[20:23], v[164:167], v[210:213], v[20:23]
	v_mfma_f32_16x16x32_bf16 v[16:19], v[182:185], v[210:213], v[16:19]
	v_mfma_f32_16x16x32_bf16 v[4:7], v[164:167], v[222:225], v[4:7]
	v_mfma_f32_16x16x32_bf16 v[0:3], v[182:185], v[222:225], v[0:3]
	v_mfma_f32_16x16x32_bf16 v[52:55], v[178:181], v[194:197], v[52:55]
	v_mfma_f32_16x16x32_bf16 v[48:51], v[186:189], v[194:197], v[48:51]
	v_mfma_f32_16x16x32_bf16 v[36:39], v[178:181], v[206:209], v[36:39]
	v_mfma_f32_16x16x32_bf16 v[32:35], v[186:189], v[206:209], v[32:35]
	v_mfma_f32_16x16x32_bf16 v[20:23], v[178:181], v[214:217], v[20:23]
	v_mfma_f32_16x16x32_bf16 v[16:19], v[186:189], v[214:217], v[16:19]
	v_mfma_f32_16x16x32_bf16 v[4:7], v[178:181], v[226:229], v[4:7]
	v_mfma_f32_16x16x32_bf16 v[0:3], v[186:189], v[226:229], v[0:3]
	s_setprio 0
	s_barrier
	s_mov_b32 s100, 0
	s_add_i32 s47, s47, 2
	s_add_u32 s4, s4, 0x100
	s_addc_u32 s5, s5, 0
	s_add_u32 s45, s45, 0x100
	s_addc_u32 s46, s46, 0
	s_cmp_gt_u32 s47, 29
	s_cbranch_scc0 .LBB0_370
	s_and_b64 vcc, exec, s[18:19]
	s_cbranch_vccnz .LBB0_375
	s_add_u32 s98, s29, 0x80080
	s_addc_u32 s99, s10, 0
	v_lshl_add_u64 v[252:253], s[98:99], 0, v[146:147]
	s_add_i32 m0, s1, 0xc000
	s_nop 0
	global_load_lds_dwordx4 v[252:253], off
	v_lshl_add_u64 v[252:253], s[98:99], 0, v[148:149]
	s_add_i32 m0, s1, 0xe000
	s_nop 0
	global_load_lds_dwordx4 v[252:253], off
	s_mov_b32 s100, 1
	s_cmp_gt_i32 s36, 7
	s_mov_b64 s[4:5], -1
	s_cbranch_scc1 .LBB0_376

; #define PG8_STAGE(bufoff, gbase, voff) do { _Pragma("unroll") for (int _i = 0; _i < 2; ++_i) \
;         __builtin_amdgcn_global_load_lds((const unsigned*)((const char*)(gbase) + (voff)[_i]), (PG8_LAS unsigned*)(lds + (bufoff) + ldsw + _i * 8192), 16, 0, 0); } while (0)
; #define PG8_LDA(dst, b, h) do { _Pragma("unroll") for (int m = 0; m < 4; ++m) _Pragma("unroll") for (int k = 0; k < 2; ++k) dst[m][k] = *(const PG8_LAS bf16x8*)(lds + PG8_SA(b, h) + aoff + m * 2048 + k * 1024); } while (0)
; #define PG8_LDB(dst, b, h) do { _Pragma("unroll") for (int n = 0; n < 2; ++n) _Pragma("unroll") for (int k = 0; k < 2; ++k) dst[n][k] = *(const PG8_LAS bf16x8*)(lds + PG8_SB(b, h) + boff + n * 2048 + k * 1024); } while (0)
; #define PG8_BAR __builtin_amdgcn_s_barrier()
; #define PG8_SCHED __builtin_amdgcn_sched_barrier(0)
; template <class Epi, class Sched, bool ALIGN_EPI = false, bool SP2 = false>
; __device__ __forceinline__ void gemm_phase(PG8_LAS unsigned char* lds, const Gemm g, const Sched& S, const Epi& E) {
;     ...
;             const char* a1 = cA + (size_t)(t + 1) * kstep;
;             const char* a2 = last ? nA : cA + (size_t)(t + 2) * kstep; const char* b2 = last ? nB : cB + (size_t)(t + 2) * kstep;
;             const char* a3 = a2 + kstep; const char* b3 = b2 + kstep;
;             if (last && has_next) S.a_ready(nxt);
;             if constexpr (SP2) {
;             PG8_LDB(B0, 0, 0); PG8_LDB(B1, 0, 1); PG8_SCHED; PG8_LDA(At, 0, 0); PG8_STAGE(PG8_SA(1, 1), a1 + hstep, voffA);
;     ...
;         if constexpr (ALIGN_EPI) { if (wr == 0) PG8_BAR; }
;         if constexpr (!Epi::AFTER_DRAIN) { E(acc, cur, wr, wc, fr, fq); S.done(cur); }
.LBB0_375:
	s_barrier
	s_add_u32 s98, s29, 0x80080
	s_addc_u32 s99, s10, 0
	v_lshl_add_u64 v[252:253], s[98:99], 0, v[146:147]
	s_add_i32 m0, s1, 0xc000
	s_nop 0
	global_load_lds_dwordx4 v[252:253], off
	v_lshl_add_u64 v[252:253], s[98:99], 0, v[148:149]
	s_add_i32 m0, s1, 0xe000
	s_nop 0
	global_load_lds_dwordx4 v[252:253], off
	s_mov_b32 s100, 1
	s_cmp_gt_i32 s36, 7
	s_mov_b64 s[4:5], -1
	s_cbranch_scc0 .LBB0_373

; #define PG8_STAGE(bufoff, gbase, voff) do { _Pragma("unroll") for (int _i = 0; _i < 2; ++_i) \
;         __builtin_amdgcn_global_load_lds((const unsigned*)((const char*)(gbase) + (voff)[_i]), (PG8_LAS unsigned*)(lds + (bufoff) + ldsw + _i * 8192), 16, 0, 0); } while (0)
; #define PG8_WAIT_V(n) asm volatile("s_waitcnt vmcnt(" #n ")" ::: "memory")
; #define PG8_BAR __builtin_amdgcn_s_barrier()
;     __host__ __device__ bool next(int i, Unit& u) const {
;         const long L = (long)i * G + c; if (L >= nwg) return false;
;         int wgid = (int)L; { const int q = nwg / NXCD, r = nwg % NXCD, xcd = wgid % NXCD, off = wgid / NXCD; wgid = (xcd < r ? xcd * (q + 1) : r * (q + 1) + (xcd - r) * q) + off; }
;         const int nig = WGM * nN, gid = wgid / nig, fm = gid * WGM, gsz = (nM - fm) < WGM ? (nM - fm) : WGM;
;         u.pm = fm + ((wgid % nig) % gsz); u.pn = (wgid % nig) / gsz; return true;
;     }
; template <class Epi, class Sched, bool ALIGN_EPI = false, bool SP2 = false>
; __device__ __forceinline__ void gemm_phase(PG8_LAS unsigned char* lds, const Gemm g, const Sched& S, const Epi& E) {
;     ...
;     if constexpr (SP2) {
;         PG8_STAGE(PG8_SB(0, 0), cB, voffB); PG8_STAGE(PG8_SB(0, 1), cB + hstep, voffB); PG8_STAGE(PG8_SA(0, 0), cA, voffA); PG8_STAGE(PG8_SA(0, 1), cA + hstep, voffA);
;         if (wr == 1) PG8_BAR;
;         PG8_WAIT_V(2); PG8_BAR;
;         PG8_STAGE(PG8_SB(1, 0), cB + kstep, voffB); PG8_STAGE(PG8_SA(1, 0), cA + kstep, voffA); PG8_STAGE(PG8_SB(1, 1), cB + hstep + kstep, voffB);
;         PG8_WAIT_V(6); PG8_BAR;
.LBB0_1066:
	s_cmp_lt_i32 s66, 8
	s_cselect_b64 s[2:3], -1, 0
	s_add_u32 s6, s64, 0x15f00000
	s_addc_u32 s7, s65, 0
	s_and_b64 s[8:9], s[2:3], s[0:1]
	s_andn2_b64 vcc, exec, s[8:9]
	s_cbranch_vccnz .LBB0_1130
	s_mov_b32 s100, 0
	v_lshlrev_b32_e32 v0, 4, v220
	s_waitcnt lgkmcnt(0)
	v_and_b32_e32 v1, 32, v220
	v_bitop3_b32 v146, v0, v1, 48 bitop3:0x6c
	v_lshrrev_b32_e32 v1, 1, v220
	v_and_b32_e32 v8, 24, v1
	v_lshrrev_b32_e32 v1, 5, v220
	v_and_b32_e32 v1, 4, v1
	v_bfe_u32 v2, v220, 2, 2
	v_or3_b32 v1, v1, v2, v8
	v_lshrrev_b32_e32 v2, 3, v220
	s_movk_i32 s0, 0x60
	v_add_u32_e32 v9, 0x2000, v0
	v_and_or_b32 v156, v2, s0, v1
	v_lshrrev_b32_e32 v0, 7, v9
	s_movk_i32 s0, 0xe0
	v_and_b32_e32 v149, 0xf0, v0
	v_and_or_b32 v158, v0, s0, v1
	v_lshlrev_b32_e32 v0, 6, v220
	v_bfe_u32 v148, v220, 2, 4
	v_and_b32_e32 v147, 64, v220
	v_and_b32_e32 v150, 0x70, v2
	v_and_b32_e32 v151, 0x3c0, v0
	v_lshlrev_b32_e32 v0, 2, v220
	v_readfirstlane_b32 s1, v220
	v_or_b32_e32 v154, v146, v147
	v_or_b32_e32 v155, v150, v148
	v_or_b32_e32 v157, v149, v148
	v_and_b32_e32 v153, 15, v220
	s_cmpk_gt_i32 s77, 0xaff
	v_and_b32_e32 v152, 32, v0
	s_cbranch_scc1 .LBB0_1083
	s_ashr_i32 s31, s77, 31
	s_lshr_b32 s0, s31, 29
	s_add_i32 s0, s77, s0
	s_lshr_b32 s12, s1, 6
	s_ashr_i32 s2, s0, 3
	s_and_b32 s0, s0, -8
	s_lshr_b32 s14, s1, 8
	s_lshl_b32 s30, s12, 10
	s_sub_i32 s0, s77, s0
	s_cmp_lt_i32 s0, 0
	s_movk_i32 s33, 0x161
	s_cselect_b32 s3, s33, 0x160
	s_mul_i32 s0, s0, s3
	s_add_i32 s0, s0, s2
	s_mul_hi_i32 s2, s0, 0x2e8ba2e9
	s_lshr_b32 s3, s2, 31
	s_ashr_i32 s2, s2, 5
	s_add_i32 s2, s2, s3
	s_lshl_b32 s3, s2, 2
	s_mulk_i32 s2, 0xb0
	s_sub_i32 s2, s0, s2
	s_sext_i32_i16 s0, s2
	s_bfe_u32 s0, s0, 0x2001d
	s_add_i32 s4, s2, s0
	s_sext_i32_i16 s0, s4
	s_and_b32 s4, s4, 0xfffc
	s_sub_i32 s2, s2, s4
	s_sext_i32_i16 s2, s2
	s_lshr_b32 s0, s0, 2
	s_add_i32 s2, s3, s2
	s_ashr_i32 s3, s2, 31
	s_bfe_i64 s[10:11], s[0:1], 0x100000
	s_lshl_b64 s[4:5], s[2:3], 20
	s_lshl_b64 s[10:11], s[10:11], 20
	s_add_u32 s26, s86, s10
	s_addc_u32 s27, s87, s11
	s_add_i32 s34, s30, 0
	v_lshl_or_b32 v132, v156, 12, v154
	s_add_i32 m0, s34, 0x10000
	v_lshl_or_b32 v128, v158, 12, v154
	global_load_lds_dwordx4 v132, s[26:27]
	s_add_i32 m0, s34, 0x12000
	s_add_u32 s10, s26, 0x80000
	global_load_lds_dwordx4 v128, s[26:27]
	s_addc_u32 s11, s27, 0
	s_add_i32 m0, s34, 0x14000
	v_lshl_or_b32 v134, v155, 12, v154
	global_load_lds_dwordx4 v132, s[10:11]
	s_add_i32 m0, s34, 0x16000
	s_add_u32 s24, s80, s4
	s_addc_u32 s25, s81, s5
	s_add_i32 s35, s34, 0x2000
	global_load_lds_dwordx4 v128, s[10:11]
	s_mov_b32 m0, s34
	s_add_u32 s4, s24, 0x80000
	v_lshl_or_b32 v130, v157, 12, v154
	global_load_lds_dwordx4 v134, s[24:25]
	s_mov_b32 m0, s35
	s_addc_u32 s5, s25, 0
	s_add_i32 s36, s34, 0x4000
	global_load_lds_dwordx4 v130, s[24:25]
	s_mov_b32 m0, s36
	s_add_i32 s37, s34, 0x6000
	global_load_lds_dwordx4 v134, s[4:5]
	s_mov_b32 m0, s37
	v_mov_b32_e32 v133, 0
	global_load_lds_dwordx4 v130, s[4:5]
	v_mov_b32_e32 v129, v133
	v_mov_b32_e32 v135, v133
	v_mov_b32_e32 v131, v133
	s_cmp_eq_u32 s14, 1
	s_mov_b32 s38, 0
	v_lshl_add_u64 v[6:7], s[26:27], 0, v[132:133]
	v_lshl_add_u64 v[4:5], s[26:27], 0, v[128:129]
	v_lshl_add_u64 v[0:1], s[24:25], 0, v[134:135]
	s_cselect_b64 s[4:5], -1, 0
	s_cmp_lg_u32 s14, 1
	v_lshl_add_u64 v[2:3], s[24:25], 0, v[130:131]
	s_cbranch_scc1 .LBB0_1070
	s_barrier

; #define PG8_STAGE(bufoff, gbase, voff) do { _Pragma("unroll") for (int _i = 0; _i < 2; ++_i) \
;         __builtin_amdgcn_global_load_lds((const unsigned*)((const char*)(gbase) + (voff)[_i]), (PG8_LAS unsigned*)(lds + (bufoff) + ldsw + _i * 8192), 16, 0, 0); } while (0)
; #define PG8_LDA(dst, b, h) do { _Pragma("unroll") for (int m = 0; m < 4; ++m) _Pragma("unroll") for (int k = 0; k < 2; ++k) dst[m][k] = *(const PG8_LAS bf16x8*)(lds + PG8_SA(b, h) + aoff + m * 2048 + k * 1024); } while (0)
; #define PG8_LDB(dst, b, h) do { _Pragma("unroll") for (int n = 0; n < 2; ++n) _Pragma("unroll") for (int k = 0; k < 2; ++k) dst[n][k] = *(const PG8_LAS bf16x8*)(lds + PG8_SB(b, h) + boff + n * 2048 + k * 1024); } while (0)
; #define PG8_MMA(ai, bj, At, Bt) do { __builtin_amdgcn_s_setprio(1); _Pragma("unroll") for (int m = 0; m < 4; ++m) _Pragma("unroll") for (int n = 0; n < 2; ++n) _Pragma("unroll") for (int k = 0; k < 2; ++k) \
;         acc[ai][bj][m][n] = __builtin_amdgcn_mfma_f32_16x16x32_bf16(Bt[n][k], At[m][k], acc[ai][bj][m][n], 0, 0, 0); __builtin_amdgcn_s_setprio(0); } while (0)
; #define PG8_WAIT_V(n) asm volatile("s_waitcnt vmcnt(" #n ")" ::: "memory")
; #define PG8_BAR __builtin_amdgcn_s_barrier()
; template <class Epi, class Sched, bool ALIGN_EPI = false, bool SP2 = false>
; __device__ __forceinline__ void gemm_phase(PG8_LAS unsigned char* lds, const Gemm g, const Sched& S, const Epi& E) {
;     ...
;         for (int t = 0; t < nt; t += 2) {
;             const bool last = (t == nt - 2);
;             const char* a1 = cA + (size_t)(t + 1) * kstep;
;             const char* a2 = last ? nA : cA + (size_t)(t + 2) * kstep; const char* b2 = last ? nB : cB + (size_t)(t + 2) * kstep;
;             const char* a3 = a2 + kstep; const char* b3 = b2 + kstep;
;             if (last && has_next) S.a_ready(nxt);
;             if constexpr (SP2) {
;             PG8_LDB(B0, 0, 0); PG8_LDB(B1, 0, 1); PG8_SCHED; PG8_LDA(At, 0, 0); PG8_STAGE(PG8_SA(1, 1), a1 + hstep, voffA);
;             PG8_WAIT_V(8); PG8_WAIT_L(0); PG8_BAR; PG8_MMA(0, 0, At, B0); PG8_MMA(0, 1, At, B1); PG8_BAR; PG8_SCHED;
;             PG8_LDA(At, 0, 1); PG8_STAGE(PG8_SB(0, 0), b2, voffB); PG8_STAGE(PG8_SB(0, 1), b2 + hstep, voffB); PG8_STAGE(PG8_SA(0, 0), a2, voffA);
;             PG8_WAIT_V(8); PG8_WAIT_L(0); PG8_BAR; PG8_MMA(1, 0, At, B0); PG8_MMA(1, 1, At, B1); PG8_BAR; PG8_SCHED;
.LBB0_1076:
	ds_read_b128 v[166:169], v162
	ds_read_b128 v[170:173], v162 offset:1024
	ds_read_b128 v[174:177], v162 offset:2048
	ds_read_b128 v[178:181], v162 offset:3072
	ds_read_b128 v[182:185], v163
	ds_read_b128 v[186:189], v163 offset:1024
	ds_read_b128 v[190:193], v163 offset:2048
	ds_read_b128 v[194:197], v163 offset:3072
	s_add_u32 s26, s24, 0xfff80080
	s_addc_u32 s27, s25, -1
	s_cmp_eq_u32 s51, 28
	s_cselect_b32 s29, s19, s27
	s_cselect_b32 s28, s47, s26
	s_cselect_b32 s27, s17, s50
	s_cselect_b32 s26, s48, s49
	v_lshl_add_u64 v[144:145], s[24:25], 0, v[136:137]
	s_add_i32 m0, s34, 0xc000
	ds_read_b128 v[198:201], v164
	ds_read_b128 v[202:205], v164 offset:1024
	ds_read_b128 v[206:209], v164 offset:2048
	ds_read_b128 v[210:213], v164 offset:3072
	ds_read_b128 v[214:217], v164 offset:4096
	ds_read_b128 v[222:225], v164 offset:5120
	ds_read_b128 v[226:229], v164 offset:6144
	ds_read_b128 v[230:233], v164 offset:7168
	s_cmp_lg_u32 s100, 0
	s_cbranch_scc1 .Lgr_p7_0
	global_load_lds_dwordx4 v[144:145], off
	v_lshl_add_u64 v[144:145], s[24:25], 0, v[138:139]
	s_add_i32 m0, s34, 0xe000
	s_nop 0
	global_load_lds_dwordx4 v[144:145], off
	s_waitcnt vmcnt(8)
.Lgr_p7_0:
	s_waitcnt lgkmcnt(0)
	s_barrier
	s_setprio 1
	s_waitcnt lgkmcnt(0)
	v_mfma_f32_16x16x32_bf16 v[116:119], v[166:169], v[198:201], v[116:119]
	v_mfma_f32_16x16x32_bf16 v[112:115], v[174:177], v[198:201], v[112:115]
	v_mfma_f32_16x16x32_bf16 v[108:111], v[166:169], v[206:209], v[108:111]
	v_mfma_f32_16x16x32_bf16 v[100:103], v[174:177], v[206:209], v[100:103]
	v_mfma_f32_16x16x32_bf16 v[92:95], v[166:169], v[214:217], v[92:95]
	v_mfma_f32_16x16x32_bf16 v[84:87], v[174:177], v[214:217], v[84:87]
	v_mfma_f32_16x16x32_bf16 v[76:79], v[166:169], v[226:229], v[76:79]
	v_mfma_f32_16x16x32_bf16 v[68:71], v[174:177], v[226:229], v[68:71]
	v_mfma_f32_16x16x32_bf16 v[116:119], v[170:173], v[202:205], v[116:119]
	v_mfma_f32_16x16x32_bf16 v[112:115], v[178:181], v[202:205], v[112:115]
	v_mfma_f32_16x16x32_bf16 v[108:111], v[170:173], v[210:213], v[108:111]
	v_mfma_f32_16x16x32_bf16 v[100:103], v[178:181], v[210:213], v[100:103]
	v_mfma_f32_16x16x32_bf16 v[92:95], v[170:173], v[222:225], v[92:95]
	v_mfma_f32_16x16x32_bf16 v[84:87], v[178:181], v[222:225], v[84:87]
	v_mfma_f32_16x16x32_bf16 v[76:79], v[170:173], v[230:233], v[76:79]
	v_mfma_f32_16x16x32_bf16 v[68:71], v[178:181], v[230:233], v[68:71]
	s_setprio 0
	s_setprio 1
	v_mfma_f32_16x16x32_bf16 v[124:127], v[182:185], v[198:201], v[124:127]
	v_mfma_f32_16x16x32_bf16 v[120:123], v[190:193], v[198:201], v[120:123]
	v_mfma_f32_16x16x32_bf16 v[104:107], v[182:185], v[206:209], v[104:107]
	v_mfma_f32_16x16x32_bf16 v[96:99], v[190:193], v[206:209], v[96:99]
	v_mfma_f32_16x16x32_bf16 v[88:91], v[182:185], v[214:217], v[88:91]
	v_mfma_f32_16x16x32_bf16 v[80:83], v[190:193], v[214:217], v[80:83]
	v_mfma_f32_16x16x32_bf16 v[72:75], v[182:185], v[226:229], v[72:75]
	v_mfma_f32_16x16x32_bf16 v[64:67], v[190:193], v[226:229], v[64:67]
	v_mfma_f32_16x16x32_bf16 v[124:127], v[186:189], v[202:205], v[124:127]
	v_mfma_f32_16x16x32_bf16 v[120:123], v[194:197], v[202:205], v[120:123]
	v_mfma_f32_16x16x32_bf16 v[104:107], v[186:189], v[210:213], v[104:107]
	v_mfma_f32_16x16x32_bf16 v[96:99], v[194:197], v[210:213], v[96:99]
	v_mfma_f32_16x16x32_bf16 v[88:91], v[186:189], v[222:225], v[88:91]
	v_mfma_f32_16x16x32_bf16 v[80:83], v[194:197], v[222:225], v[80:83]
	v_mfma_f32_16x16x32_bf16 v[72:75], v[186:189], v[230:233], v[72:75]
	v_mfma_f32_16x16x32_bf16 v[64:67], v[194:197], v[230:233], v[64:67]
	s_setprio 0
	s_barrier
	s_add_i32 s52, s43, s30
	v_lshl_add_u64 v[144:145], s[26:27], 0, v[132:133]
	s_mov_b32 m0, s52
	ds_read_b128 v[198:201], v164 offset:16384
	ds_read_b128 v[202:205], v164 offset:17408
	ds_read_b128 v[206:209], v164 offset:18432
	ds_read_b128 v[210:213], v164 offset:19456
	ds_read_b128 v[214:217], v164 offset:20480
	ds_read_b128 v[222:225], v164 offset:21504
	ds_read_b128 v[226:229], v164 offset:22528
	ds_read_b128 v[230:233], v164 offset:23552
	global_load_lds_dwordx4 v[144:145], off
	s_add_i32 m0, s52, 0x2000
	s_add_u32 s52, s26, 0x80000
	v_lshl_add_u64 v[218:219], s[26:27], 0, v[128:129]
	s_addc_u32 s53, s27, 0
	s_add_i32 s54, s44, s30
	global_load_lds_dwordx4 v[218:219], off
	v_lshl_add_u64 v[234:235], s[52:53], 0, v[132:133]
	s_mov_b32 m0, s54
	v_lshl_add_u64 v[236:237], s[28:29], 0, v[130:131]
	global_load_lds_dwordx4 v[234:235], off
	v_lshl_add_u64 v[234:235], s[52:53], 0, v[128:129]
	s_add_i32 m0, s54, 0x2000
	s_nop 0
	global_load_lds_dwordx4 v[234:235], off
	v_lshl_add_u64 v[234:235], s[28:29], 0, v[134:135]
	s_mov_b32 m0, s34
	s_nop 0
	global_load_lds_dwordx4 v[234:235], off
	s_mov_b32 m0, s35
	s_nop 0
	global_load_lds_dwordx4 v[236:237], off
	s_cmp_lg_u32 s100, 0
	s_cbranch_scc1 .Lgr_p7_1
	s_waitcnt vmcnt(8)
; #define PG8_STAGE(bufoff, gbase, voff) do { _Pragma("unroll") for (int _i = 0; _i < 2; ++_i) \
;         __builtin_amdgcn_global_load_lds((const unsigned*)((const char*)(gbase) + (voff)[_i]), (PG8_LAS unsigned*)(lds + (bufoff) + ldsw + _i * 8192), 16, 0, 0); } while (0)
; #define PG8_LDA(dst, b, h) do { _Pragma("unroll") for (int m = 0; m < 4; ++m) _Pragma("unroll") for (int k = 0; k < 2; ++k) dst[m][k] = *(const PG8_LAS bf16x8*)(lds + PG8_SA(b, h) + aoff + m * 2048 + k * 1024); } while (0)
; #define PG8_LDB(dst, b, h) do { _Pragma("unroll") for (int n = 0; n < 2; ++n) _Pragma("unroll") for (int k = 0; k < 2; ++k) dst[n][k] = *(const PG8_LAS bf16x8*)(lds + PG8_SB(b, h) + boff + n * 2048 + k * 1024); } while (0)
; #define PG8_MMA(ai, bj, At, Bt) do { __builtin_amdgcn_s_setprio(1); _Pragma("unroll") for (int m = 0; m < 4; ++m) _Pragma("unroll") for (int n = 0; n < 2; ++n) _Pragma("unroll") for (int k = 0; k < 2; ++k) \
;         acc[ai][bj][m][n] = __builtin_amdgcn_mfma_f32_16x16x32_bf16(Bt[n][k], At[m][k], acc[ai][bj][m][n], 0, 0, 0); __builtin_amdgcn_s_setprio(0); } while (0)
; #define PG8_WAIT_V(n) asm volatile("s_waitcnt vmcnt(" #n ")" ::: "memory")
; #define PG8_WAIT_L(n) asm volatile("s_waitcnt lgkmcnt(" #n ")" ::: "memory")
; #define PG8_BAR __builtin_amdgcn_s_barrier()
; #define PG8_SCHED __builtin_amdgcn_sched_barrier(0)
; template <class Epi, class Sched, bool ALIGN_EPI = false, bool SP2 = false>
; __device__ __forceinline__ void gemm_phase(PG8_LAS unsigned char* lds, const Gemm g, const Sched& S, const Epi& E) {
;     ...
;             PG8_WAIT_V(8); PG8_WAIT_L(0); PG8_BAR; PG8_MMA(1, 0, At, B0); PG8_MMA(1, 1, At, B1); PG8_BAR; PG8_SCHED;
;             PG8_LDB(B0, 1, 0); PG8_LDB(B1, 1, 1); PG8_SCHED; PG8_LDA(At, 1, 0); PG8_STAGE(PG8_SA(0, 1), a2 + hstep, voffA);
;             PG8_WAIT_V(8); PG8_WAIT_L(0); PG8_BAR; PG8_MMA(0, 0, At, B0); PG8_MMA(0, 1, At, B1); PG8_BAR; PG8_SCHED;
.Lgr_p7_1:
	s_waitcnt lgkmcnt(0)
	s_barrier
	s_setprio 1
	s_waitcnt lgkmcnt(0)
	v_mfma_f32_16x16x32_bf16 v[60:63], v[166:169], v[198:201], v[60:63]
	v_mfma_f32_16x16x32_bf16 v[52:55], v[174:177], v[198:201], v[52:55]
	v_mfma_f32_16x16x32_bf16 v[44:47], v[166:169], v[206:209], v[44:47]
	v_mfma_f32_16x16x32_bf16 v[36:39], v[174:177], v[206:209], v[36:39]
	v_mfma_f32_16x16x32_bf16 v[28:31], v[166:169], v[214:217], v[28:31]
	v_mfma_f32_16x16x32_bf16 v[20:23], v[174:177], v[214:217], v[20:23]
	v_mfma_f32_16x16x32_bf16 v[12:15], v[166:169], v[226:229], v[12:15]
	v_mfma_f32_16x16x32_bf16 v[4:7], v[174:177], v[226:229], v[4:7]
	v_mfma_f32_16x16x32_bf16 v[60:63], v[170:173], v[202:205], v[60:63]
	v_mfma_f32_16x16x32_bf16 v[52:55], v[178:181], v[202:205], v[52:55]
	v_mfma_f32_16x16x32_bf16 v[44:47], v[170:173], v[210:213], v[44:47]
	v_mfma_f32_16x16x32_bf16 v[36:39], v[178:181], v[210:213], v[36:39]
	v_mfma_f32_16x16x32_bf16 v[28:31], v[170:173], v[222:225], v[28:31]
	v_mfma_f32_16x16x32_bf16 v[20:23], v[178:181], v[222:225], v[20:23]
	v_mfma_f32_16x16x32_bf16 v[12:15], v[170:173], v[230:233], v[12:15]
	v_mfma_f32_16x16x32_bf16 v[4:7], v[178:181], v[230:233], v[4:7]
	s_setprio 0
	s_setprio 1
	v_mfma_f32_16x16x32_bf16 v[56:59], v[182:185], v[198:201], v[56:59]
	v_mfma_f32_16x16x32_bf16 v[48:51], v[190:193], v[198:201], v[48:51]
	v_mfma_f32_16x16x32_bf16 v[40:43], v[182:185], v[206:209], v[40:43]
	v_mfma_f32_16x16x32_bf16 v[32:35], v[190:193], v[206:209], v[32:35]
	v_mfma_f32_16x16x32_bf16 v[24:27], v[182:185], v[214:217], v[24:27]
	v_mfma_f32_16x16x32_bf16 v[16:19], v[190:193], v[214:217], v[16:19]
	v_mfma_f32_16x16x32_bf16 v[8:11], v[182:185], v[226:229], v[8:11]
	v_mfma_f32_16x16x32_bf16 v[0:3], v[190:193], v[226:229], v[0:3]
	v_mfma_f32_16x16x32_bf16 v[56:59], v[186:189], v[202:205], v[56:59]
	v_mfma_f32_16x16x32_bf16 v[48:51], v[194:197], v[202:205], v[48:51]
	v_mfma_f32_16x16x32_bf16 v[40:43], v[186:189], v[210:213], v[40:43]
	v_mfma_f32_16x16x32_bf16 v[32:35], v[194:197], v[210:213], v[32:35]
	v_mfma_f32_16x16x32_bf16 v[24:27], v[186:189], v[222:225], v[24:27]
	v_mfma_f32_16x16x32_bf16 v[16:19], v[194:197], v[222:225], v[16:19]
	v_mfma_f32_16x16x32_bf16 v[8:11], v[186:189], v[230:233], v[8:11]
	v_mfma_f32_16x16x32_bf16 v[0:3], v[194:197], v[230:233], v[0:3]
	s_setprio 0
	s_barrier
	s_add_i32 s52, 0, 0x18000
	s_add_i32 s53, 0, 0x1c000
	v_add_u32_e32 v178, s52, v160
	v_add_u32_e32 v194, s53, v160
	ds_read_b128 v[166:169], v178
	ds_read_b128 v[170:173], v178 offset:1024
	ds_read_b128 v[174:177], v178 offset:2048
	ds_read_b128 v[178:181], v178 offset:3072
	ds_read_b128 v[182:185], v194
	ds_read_b128 v[186:189], v194 offset:1024
	ds_read_b128 v[190:193], v194 offset:2048
	ds_read_b128 v[194:197], v194 offset:3072
	s_add_u32 s28, s28, 0x80000
	s_addc_u32 s29, s29, 0
	s_mov_b32 m0, s36
	v_lshl_add_u64 v[238:239], s[28:29], 0, v[134:135]
	ds_read_b128 v[198:201], v164 offset:32768
	ds_read_b128 v[202:205], v164 offset:33792
	ds_read_b128 v[206:209], v164 offset:34816
	ds_read_b128 v[210:213], v164 offset:35840
	ds_read_b128 v[214:217], v164 offset:36864
	ds_read_b128 v[222:225], v164 offset:37888
	ds_read_b128 v[226:229], v164 offset:38912
	ds_read_b128 v[230:233], v164 offset:39936
	global_load_lds_dwordx4 v[238:239], off
	v_lshl_add_u64 v[238:239], s[28:29], 0, v[130:131]
	s_mov_b32 m0, s37
	s_nop 0
	global_load_lds_dwordx4 v[238:239], off
	s_cmp_lg_u32 s100, 0
	s_cbranch_scc1 .Lgr_p7_2
	s_waitcnt vmcnt(8)
.Lgr_p7_2:
	s_waitcnt lgkmcnt(0)
	s_barrier
	s_setprio 1
	s_waitcnt lgkmcnt(0)
	v_mfma_f32_16x16x32_bf16 v[116:119], v[166:169], v[198:201], v[116:119]
	v_mfma_f32_16x16x32_bf16 v[112:115], v[174:177], v[198:201], v[112:115]
	v_mfma_f32_16x16x32_bf16 v[108:111], v[166:169], v[206:209], v[108:111]
	v_mfma_f32_16x16x32_bf16 v[100:103], v[174:177], v[206:209], v[100:103]
	v_mfma_f32_16x16x32_bf16 v[92:95], v[166:169], v[214:217], v[92:95]
	v_mfma_f32_16x16x32_bf16 v[84:87], v[174:177], v[214:217], v[84:87]
	v_mfma_f32_16x16x32_bf16 v[76:79], v[166:169], v[226:229], v[76:79]
	v_mfma_f32_16x16x32_bf16 v[68:71], v[174:177], v[226:229], v[68:71]
	v_mfma_f32_16x16x32_bf16 v[116:119], v[170:173], v[202:205], v[116:119]
	v_mfma_f32_16x16x32_bf16 v[112:115], v[178:181], v[202:205], v[112:115]
	v_mfma_f32_16x16x32_bf16 v[108:111], v[170:173], v[210:213], v[108:111]
	v_mfma_f32_16x16x32_bf16 v[100:103], v[178:181], v[210:213], v[100:103]
	v_mfma_f32_16x16x32_bf16 v[92:95], v[170:173], v[222:225], v[92:95]
	v_mfma_f32_16x16x32_bf16 v[84:87], v[178:181], v[222:225], v[84:87]
	v_mfma_f32_16x16x32_bf16 v[76:79], v[170:173], v[230:233], v[76:79]
	v_mfma_f32_16x16x32_bf16 v[68:71], v[178:181], v[230:233], v[68:71]
	s_setprio 0
	s_setprio 1
	v_mfma_f32_16x16x32_bf16 v[124:127], v[182:185], v[198:201], v[124:127]
	v_mfma_f32_16x16x32_bf16 v[120:123], v[190:193], v[198:201], v[120:123]
	v_mfma_f32_16x16x32_bf16 v[104:107], v[182:185], v[206:209], v[104:107]
	v_mfma_f32_16x16x32_bf16 v[96:99], v[190:193], v[206:209], v[96:99]
	v_mfma_f32_16x16x32_bf16 v[88:91], v[182:185], v[214:217], v[88:91]
	v_mfma_f32_16x16x32_bf16 v[80:83], v[190:193], v[214:217], v[80:83]
	v_mfma_f32_16x16x32_bf16 v[72:75], v[182:185], v[226:229], v[72:75]
	v_mfma_f32_16x16x32_bf16 v[64:67], v[190:193], v[226:229], v[64:67]
	v_mfma_f32_16x16x32_bf16 v[124:127], v[186:189], v[202:205], v[124:127]
	v_mfma_f32_16x16x32_bf16 v[120:123], v[194:197], v[202:205], v[120:123]
	v_mfma_f32_16x16x32_bf16 v[104:107], v[186:189], v[210:213], v[104:107]
	v_mfma_f32_16x16x32_bf16 v[96:99], v[194:197], v[210:213], v[96:99]
	v_mfma_f32_16x16x32_bf16 v[88:91], v[186:189], v[222:225], v[88:91]
	v_mfma_f32_16x16x32_bf16 v[80:83], v[194:197], v[222:225], v[80:83]
	v_mfma_f32_16x16x32_bf16 v[72:75], v[186:189], v[230:233], v[72:75]
	v_mfma_f32_16x16x32_bf16 v[64:67], v[194:197], v[230:233], v[64:67]
	s_setprio 0
	s_barrier
; #define PG8_STAGE(bufoff, gbase, voff) do { _Pragma("unroll") for (int _i = 0; _i < 2; ++_i) \
;         __builtin_amdgcn_global_load_lds((const unsigned*)((const char*)(gbase) + (voff)[_i]), (PG8_LAS unsigned*)(lds + (bufoff) + ldsw + _i * 8192), 16, 0, 0); } while (0)
; #define PG8_LDA(dst, b, h) do { _Pragma("unroll") for (int m = 0; m < 4; ++m) _Pragma("unroll") for (int k = 0; k < 2; ++k) dst[m][k] = *(const PG8_LAS bf16x8*)(lds + PG8_SA(b, h) + aoff + m * 2048 + k * 1024); } while (0)
; #define PG8_WAIT_V(n) asm volatile("s_waitcnt vmcnt(" #n ")" ::: "memory")
; #define PG8_WAIT_L(n) asm volatile("s_waitcnt lgkmcnt(" #n ")" ::: "memory")
; #define PG8_BAR __builtin_amdgcn_s_barrier()
; #define PG8_SCHED __builtin_amdgcn_sched_barrier(0)
; template <class Epi, class Sched, bool ALIGN_EPI = false, bool SP2 = false>
; __device__ __forceinline__ void gemm_phase(PG8_LAS unsigned char* lds, const Gemm g, const Sched& S, const Epi& E) {
;     ...
;             PG8_LDA(At, 1, 1); PG8_STAGE(PG8_SB(1, 0), b3, voffB); PG8_STAGE(PG8_SB(1, 1), b3 + hstep, voffB); PG8_STAGE(PG8_SA(1, 0), a3, voffA);
;             PG8_WAIT_V(8); PG8_WAIT_L(0); PG8_BAR; PG8_MMA(1, 0, At, B0); PG8_MMA(1, 1, At, B1); PG8_BAR; PG8_SCHED;
;     __device__ __forceinline__ void operator()(const pg8::f32x4 (&acc)[2][2][4][2], const pg8::Unit& u, int wr, int wc, int fr, int fq) const {
;         const int col0 = u.pn * 128 + wc * 32 + 8 * fq, row0 = u.pm * 256 + wr * 64 + fr;
;         float rsv[2][4];
; #pragma unroll
;         for (int ai = 0; ai < 2; ++ai)
; #pragma unroll
;             for (int m = 0; m < 4; ++m) rsv[ai][m] = ss[row0 + ai * 128 + m * 16];
; #pragma unroll
;         for (int ai = 0; ai < 2; ++ai)
; #pragma unroll
;             for (int m = 0; m < 4; ++m) {
;                 const int row = row0 + ai * 128 + m * 16;
;                 const float rs = rsqrtf(rsv[ai][m] * (1.f / DM) + EPS), c1 = -rs * LOG2E, rs2 = rs * rs;
;                 u32x4 w;
; #pragma unroll
;                 for (int n = 0; n < 2; ++n) {
;                     const pg8::f32x4 g = acc[ai][0][m][n], up = acc[ai][1][m][n];
;                     float o4[4];
; #pragma unroll
;                     for (int k = 0; k < 4; ++k) o4[k] = (g[k] * up[k]) * (rs2 * __builtin_amdgcn_rcpf(1.f + __builtin_amdgcn_exp2f(g[k] * c1)));
	s_add_i32 s28, s52, s30
	v_lshl_add_u64 v[144:145], v[144:145], 0, s[12:13]
	s_mov_b32 m0, s28
	ds_read_b128 v[198:201], v164 offset:49152
	ds_read_b128 v[202:205], v164 offset:50176
	ds_read_b128 v[206:209], v164 offset:51200
	ds_read_b128 v[210:213], v164 offset:52224
	ds_read_b128 v[214:217], v164 offset:53248
	ds_read_b128 v[222:225], v164 offset:54272
	ds_read_b128 v[226:229], v164 offset:55296
	ds_read_b128 v[230:233], v164 offset:56320
	global_load_lds_dwordx4 v[144:145], off
	s_add_i32 m0, s28, 0x2000
	s_add_u32 s26, s26, 0x80080
	v_lshl_add_u64 v[144:145], v[218:219], 0, s[12:13]
	s_addc_u32 s27, s27, 0
	s_add_i32 s28, s53, s30
	global_load_lds_dwordx4 v[144:145], off
	v_lshl_add_u64 v[144:145], s[26:27], 0, v[132:133]
	s_mov_b32 m0, s28
	s_nop 0
	global_load_lds_dwordx4 v[144:145], off
	v_lshl_add_u64 v[144:145], s[26:27], 0, v[128:129]
	s_add_i32 m0, s28, 0x2000
	s_nop 0
	global_load_lds_dwordx4 v[144:145], off
	v_lshl_add_u64 v[144:145], v[234:235], 0, s[12:13]
	s_mov_b32 m0, s39
	s_nop 0
	global_load_lds_dwordx4 v[144:145], off
	v_lshl_add_u64 v[144:145], v[236:237], 0, s[12:13]
	s_mov_b32 m0, s40
	s_nop 0
	global_load_lds_dwordx4 v[144:145], off
	s_waitcnt vmcnt(8)
	s_waitcnt lgkmcnt(0)
	s_barrier
	s_setprio 1
	s_waitcnt lgkmcnt(0)
	v_mfma_f32_16x16x32_bf16 v[60:63], v[166:169], v[198:201], v[60:63]
	v_mfma_f32_16x16x32_bf16 v[52:55], v[174:177], v[198:201], v[52:55]
	v_mfma_f32_16x16x32_bf16 v[44:47], v[166:169], v[206:209], v[44:47]
	v_mfma_f32_16x16x32_bf16 v[36:39], v[174:177], v[206:209], v[36:39]
	v_mfma_f32_16x16x32_bf16 v[28:31], v[166:169], v[214:217], v[28:31]
	v_mfma_f32_16x16x32_bf16 v[20:23], v[174:177], v[214:217], v[20:23]
	v_mfma_f32_16x16x32_bf16 v[12:15], v[166:169], v[226:229], v[12:15]
	v_mfma_f32_16x16x32_bf16 v[4:7], v[174:177], v[226:229], v[4:7]
	v_mfma_f32_16x16x32_bf16 v[60:63], v[170:173], v[202:205], v[60:63]
	v_mfma_f32_16x16x32_bf16 v[52:55], v[178:181], v[202:205], v[52:55]
	v_mfma_f32_16x16x32_bf16 v[44:47], v[170:173], v[210:213], v[44:47]
	v_mfma_f32_16x16x32_bf16 v[36:39], v[178:181], v[210:213], v[36:39]
	v_mfma_f32_16x16x32_bf16 v[28:31], v[170:173], v[222:225], v[28:31]
	v_mfma_f32_16x16x32_bf16 v[20:23], v[178:181], v[222:225], v[20:23]
	v_mfma_f32_16x16x32_bf16 v[12:15], v[170:173], v[230:233], v[12:15]
	v_mfma_f32_16x16x32_bf16 v[4:7], v[178:181], v[230:233], v[4:7]
	s_setprio 0
	s_setprio 1
	v_mfma_f32_16x16x32_bf16 v[56:59], v[182:185], v[198:201], v[56:59]
	v_mfma_f32_16x16x32_bf16 v[48:51], v[190:193], v[198:201], v[48:51]
	v_mfma_f32_16x16x32_bf16 v[40:43], v[182:185], v[206:209], v[40:43]
	v_mfma_f32_16x16x32_bf16 v[32:35], v[190:193], v[206:209], v[32:35]
	v_mfma_f32_16x16x32_bf16 v[24:27], v[182:185], v[214:217], v[24:27]
	v_mfma_f32_16x16x32_bf16 v[16:19], v[190:193], v[214:217], v[16:19]
	v_mfma_f32_16x16x32_bf16 v[8:11], v[182:185], v[226:229], v[8:11]
	v_mfma_f32_16x16x32_bf16 v[0:3], v[190:193], v[226:229], v[0:3]
	v_mfma_f32_16x16x32_bf16 v[56:59], v[186:189], v[202:205], v[56:59]
	v_mfma_f32_16x16x32_bf16 v[48:51], v[194:197], v[202:205], v[48:51]
	v_mfma_f32_16x16x32_bf16 v[40:43], v[186:189], v[210:213], v[40:43]
	v_mfma_f32_16x16x32_bf16 v[32:35], v[194:197], v[210:213], v[32:35]
	v_mfma_f32_16x16x32_bf16 v[24:27], v[186:189], v[222:225], v[24:27]
	v_mfma_f32_16x16x32_bf16 v[16:19], v[194:197], v[222:225], v[16:19]
	v_mfma_f32_16x16x32_bf16 v[8:11], v[186:189], v[230:233], v[8:11]
	v_mfma_f32_16x16x32_bf16 v[0:3], v[194:197], v[230:233], v[0:3]
	s_setprio 0
	s_barrier
	s_mov_b32 s100, 0
	s_add_i32 s51, s51, 2
	s_add_u32 s24, s24, 0x100
	s_addc_u32 s25, s25, 0
	s_add_u32 s49, s49, 0x100
	s_addc_u32 s50, s50, 0
	s_cmp_gt_u32 s51, 29
	s_cbranch_scc0 .LBB0_1076
	s_and_b64 vcc, exec, s[14:15]
	s_cbranch_vccz .LBB0_1079
	s_barrier
.LBB0_1079:
	s_add_u32 s98, s47, 0x80080
	s_addc_u32 s99, s19, 0
	v_lshl_add_u64 v[252:253], s[98:99], 0, v[136:137]
	s_add_i32 m0, s34, 0xc000
	s_nop 0
	global_load_lds_dwordx4 v[252:253], off
	v_lshl_add_u64 v[252:253], s[98:99], 0, v[138:139]
	s_add_i32 m0, s34, 0xe000
	s_nop 0
	global_load_lds_dwordx4 v[252:253], off
	s_mov_b32 s100, 1
	v_lshl_add_u32 v168, s2, 8, v159
	v_ashrrev_i32_e32 v169, 31, v168
	v_lshl_add_u64 v[170:171], v[168:169], 2, s[10:11]
	v_or_b32_e32 v144, 16, v168
	global_load_dword v184, v[170:171], off
	v_ashrrev_i32_e32 v145, 31, v144
	v_lshl_add_u64 v[166:167], v[144:145], 2, s[10:11]
	global_load_dword v185, v[166:167], off
	v_lshl_or_b32 v172, s3, 7, v161
	v_pk_mul_f32 v[174:175], v[118:119], v[126:127]
	v_pk_mul_f32 v[176:177], v[116:117], v[124:125]
	v_or_b32_e32 v126, 32, v168
	v_or_b32_e32 v124, 48, v168
	v_ashrrev_i32_e32 v173, 31, v172
	v_ashrrev_i32_e32 v127, 31, v126
	v_ashrrev_i32_e32 v125, 31, v124
	v_pk_mul_f32 v[178:179], v[114:115], v[122:123]
	v_lshlrev_b64 v[122:123], 1, v[172:173]
	v_lshl_add_u64 v[172:173], v[126:127], 2, s[10:11]
	v_lshl_add_u64 v[182:183], v[124:125], 2, s[10:11]
	global_load_dword v187, v[170:171], off offset:512
	global_load_dword v188, v[170:171], off offset:576
	global_load_dword v127, v[170:171], off offset:640
	global_load_dword v189, v[172:173], off
	global_load_dword v190, v[182:183], off
	global_load_dword v125, v[170:171], off offset:704
	v_pk_mul_f32 v[180:181], v[112:113], v[120:121]
	v_mov_b64_e32 v[120:121], s[84:85]
	v_add_u32_e32 v186, 0x80, v168
	v_add_u32_e32 v167, 0x90, v168
	v_add_u32_e32 v166, 0xa0, v168
	v_add_u32_e32 v145, 0xb0, v168
	v_mad_i64_i32 v[168:169], s[2:3], v168, s46, v[120:121]
	v_lshl_add_u64 v[168:169], v[168:169], 0, v[122:123]
	v_pk_mul_f32 v[106:107], v[110:111], v[106:107]
	v_pk_mul_f32 v[104:105], v[108:109], v[104:105]
	v_pk_mul_f32 v[98:99], v[102:103], v[98:99]
	v_pk_mul_f32 v[96:97], v[100:101], v[96:97]
	v_pk_mul_f32 v[90:91], v[94:95], v[90:91]
	v_pk_mul_f32 v[88:89], v[92:93], v[88:89]
	v_pk_mul_f32 v[82:83], v[86:87], v[82:83]
	v_pk_mul_f32 v[80:81], v[84:85], v[80:81]
	v_pk_mul_f32 v[74:75], v[78:79], v[74:75]
	v_pk_mul_f32 v[72:73], v[76:77], v[72:73]
	v_pk_mul_f32 v[66:67], v[70:71], v[66:67]
	v_pk_mul_f32 v[64:65], v[68:69], v[64:65]
	v_pk_mul_f32 v[58:59], v[62:63], v[58:59]
	v_pk_mul_f32 v[56:57], v[60:61], v[56:57]
	v_pk_mul_f32 v[50:51], v[54:55], v[50:51]
	v_pk_mul_f32 v[48:49], v[52:53], v[48:49]
	v_pk_mul_f32 v[42:43], v[46:47], v[42:43]
	v_pk_mul_f32 v[40:41], v[44:45], v[40:41]
	v_pk_mul_f32 v[34:35], v[38:39], v[34:35]
	v_pk_mul_f32 v[32:33], v[36:37], v[32:33]
	v_pk_mul_f32 v[26:27], v[30:31], v[26:27]
	v_pk_mul_f32 v[24:25], v[28:29], v[24:25]
	v_pk_mul_f32 v[18:19], v[22:23], v[18:19]
	v_pk_mul_f32 v[16:17], v[20:21], v[16:17]
	v_pk_mul_f32 v[10:11], v[14:15], v[10:11]
	v_pk_mul_f32 v[8:9], v[12:13], v[8:9]
	v_pk_mul_f32 v[2:3], v[6:7], v[2:3]
	v_pk_mul_f32 v[0:1], v[4:5], v[0:1]
	s_waitcnt vmcnt(0)
; __device__ __forceinline__ unsigned cvtpk(float lo, float hi) { f32x2_t v = {lo, hi}; bf16x2_t b = __builtin_convertvector(v, bf16x2_t); return __builtin_bit_cast(unsigned, b); }
;     __device__ __forceinline__ void operator()(const pg8::f32x4 (&acc)[2][2][4][2], const pg8::Unit& u, int wr, int wc, int fr, int fq) const {
;     ...
;         for (int ai = 0; ai < 2; ++ai)
; #pragma unroll
;             for (int m = 0; m < 4; ++m) {
;                 const int row = row0 + ai * 128 + m * 16;
;                 const float rs = rsqrtf(rsv[ai][m] * (1.f / DM) + EPS), c1 = -rs * LOG2E, rs2 = rs * rs;
;                 u32x4 w;
; #pragma unroll
;                 for (int n = 0; n < 2; ++n) {
;                     const pg8::f32x4 g = acc[ai][0][m][n], up = acc[ai][1][m][n];
;                     float o4[4];
; #pragma unroll
;                     for (int k = 0; k < 4; ++k) o4[k] = (g[k] * up[k]) * (rs2 * __builtin_amdgcn_rcpf(1.f + __builtin_amdgcn_exp2f(g[k] * c1)));
;                     w[2 * n] = cvtpk(o4[0], o4[1]); w[2 * n + 1] = cvtpk(o4[2], o4[3]);
;                 }
;                 *(u32x4*)(O + (size_t)row * FF + col0) = w;
	v_fmamk_f32 v170, v184, 0x3a000000, v165
	v_mul_f32_e32 v171, 0x4b800000, v170
	v_cmp_gt_f32_e32 vcc, s45, v170
	v_fmamk_f32 v172, v185, 0x3a000000, v165
	v_cmp_gt_f32_e64 s[2:3], s45, v172
	v_cndmask_b32_e32 v170, v170, v171, vcc
	v_mul_f32_e32 v171, 0x4b800000, v172
	v_rsq_f32_e32 v170, v170
	v_cndmask_b32_e64 v171, v172, v171, s[2:3]
	v_rsq_f32_e32 v171, v171
	v_mul_f32_e32 v172, 0x45800000, v170
	v_cndmask_b32_e32 v170, v170, v172, vcc
	v_mul_f32_e32 v172, 0x45800000, v171
	v_mul_f32_e32 v173, 0xbfb8aa3b, v170
	v_cndmask_b32_e64 v171, v171, v172, s[2:3]
	v_mul_f32_e32 v172, v116, v173
	v_mul_f32_e32 v117, v117, v173
	v_mul_f32_e32 v118, v118, v173
	v_mul_f32_e32 v119, v119, v173
	v_mul_f32_e32 v112, v112, v173
	v_mul_f32_e32 v113, v113, v173
	v_mul_f32_e32 v114, v114, v173
	v_mul_f32_e32 v115, v115, v173
	v_mul_f32_e32 v184, 0xbfb8aa3b, v171
	v_mul_f32_e32 v116, v171, v171
	v_exp_f32_e32 v171, v172
	v_exp_f32_e32 v117, v117
	v_exp_f32_e32 v118, v118
	v_exp_f32_e32 v119, v119
	v_exp_f32_e32 v112, v112
	v_exp_f32_e32 v113, v113
	v_exp_f32_e32 v114, v114
	v_exp_f32_e32 v115, v115
	v_mul_f32_e32 v172, v108, v184
	v_mul_f32_e32 v173, v109, v184
	v_exp_f32_e32 v182, v172
	v_exp_f32_e32 v183, v173
	v_add_f32_e32 v171, 1.0, v171
	v_add_f32_e32 v117, 1.0, v117
	v_add_f32_e32 v118, 1.0, v118
	v_add_f32_e32 v119, 1.0, v119
	v_add_f32_e32 v172, 1.0, v112
	v_add_f32_e32 v173, 1.0, v113
	v_add_f32_e32 v191, 1.0, v114
	v_add_f32_e32 v192, 1.0, v115
	v_rcp_f32_e32 v112, v171
	v_rcp_f32_e32 v113, v117
	v_rcp_f32_e32 v114, v118
	v_rcp_f32_e32 v115, v119
	v_rcp_f32_e32 v118, v172
	v_rcp_f32_e32 v119, v173
	v_rcp_f32_e32 v172, v191
	v_rcp_f32_e32 v173, v192
	v_mul_f32_e32 v170, v170, v170
	v_add_f32_e32 v171, 1.0, v183
	v_rcp_f32_e32 v183, v171
	v_pk_mul_f32 v[112:113], v[170:171], v[112:113] op_sel_hi:[0,1]
	v_pk_mul_f32 v[114:115], v[170:171], v[114:115] op_sel_hi:[0,1]
	v_pk_mul_f32 v[118:119], v[170:171], v[118:119] op_sel_hi:[0,1]
	v_pk_mul_f32 v[170:171], v[170:171], v[172:173] op_sel_hi:[0,1]
	v_pk_mul_f32 v[112:113], v[176:177], v[112:113]
	v_pk_mul_f32 v[114:115], v[174:175], v[114:115]
	v_pk_mul_f32 v[118:119], v[180:181], v[118:119]
	v_pk_mul_f32 v[170:171], v[178:179], v[170:171]
	v_cvt_pk_bf16_f32 v112, v112, v113
	v_cvt_pk_bf16_f32 v113, v114, v115
	v_cvt_pk_bf16_f32 v114, v118, v119
	v_cvt_pk_bf16_f32 v115, v170, v171
	v_mul_f32_e32 v185, v110, v184
	global_store_dwordx4 v[168:169], v[112:115], off
	v_add_f32_e32 v117, 1.0, v182
	v_rcp_f32_e32 v182, v117
	v_mul_f32_e32 v113, v111, v184
	v_exp_f32_e32 v112, v185
	v_exp_f32_e32 v113, v113
	v_pk_mul_f32 v[108:109], v[116:117], v[182:183] op_sel_hi:[0,1]
	v_pk_mul_f32 v[104:105], v[104:105], v[108:109]
	v_add_f32_e32 v110, 1.0, v112
	v_add_f32_e32 v111, 1.0, v113
	v_rcp_f32_e32 v110, v110
	v_rcp_f32_e32 v111, v111
	v_cvt_pk_bf16_f32 v104, v104, v105
	v_mul_f32_e32 v105, v100, v184
	v_pk_mul_f32 v[108:109], v[116:117], v[110:111] op_sel_hi:[0,1]
	v_pk_mul_f32 v[106:107], v[106:107], v[108:109]
	v_exp_f32_e32 v108, v105
	v_mul_f32_e32 v105, v101, v184
	v_exp_f32_e32 v109, v105
	v_cvt_pk_bf16_f32 v105, v106, v107
	v_add_f32_e32 v106, 1.0, v108
	v_mul_f32_e32 v108, v102, v184
	v_add_f32_e32 v107, 1.0, v109
	v_mul_f32_e32 v109, v103, v184
	v_exp_f32_e32 v108, v108
	v_exp_f32_e32 v109, v109
	v_rcp_f32_e32 v106, v106
	v_rcp_f32_e32 v107, v107
	v_add_f32_e32 v102, 1.0, v108
	v_add_f32_e32 v103, 1.0, v109
	v_rcp_f32_e32 v102, v102
	v_rcp_f32_e32 v103, v103
	v_pk_mul_f32 v[100:101], v[116:117], v[106:107] op_sel_hi:[0,1]
	v_pk_mul_f32 v[96:97], v[96:97], v[100:101]
	v_pk_mul_f32 v[100:101], v[116:117], v[102:103] op_sel_hi:[0,1]
	v_cvt_pk_bf16_f32 v106, v96, v97
	v_fmamk_f32 v96, v189, 0x3a000000, v165
	v_mul_f32_e32 v97, 0x4b800000, v96
	v_cmp_gt_f32_e32 vcc, s45, v96
	v_pk_mul_f32 v[98:99], v[98:99], v[100:101]
	s_nop 0
	v_cndmask_b32_e32 v96, v96, v97, vcc
	v_cvt_pk_bf16_f32 v107, v98, v99
	v_rsq_f32_e32 v98, v96
	v_mad_i64_i32 v[96:97], s[2:3], v144, s46, v[120:121]
	v_lshl_add_u64 v[96:97], v[96:97], 0, v[122:123]
	global_store_dwordx4 v[96:97], v[104:107], off
	v_mul_f32_e32 v96, 0x45800000, v98
	v_cndmask_b32_e32 v96, v98, v96, vcc
	v_mul_f32_e32 v97, 0xbfb8aa3b, v96
	v_mul_f32_e32 v98, v92, v97
	v_mul_f32_e32 v99, v93, v97
	v_exp_f32_e32 v98, v98
	v_exp_f32_e32 v99, v99
	v_mul_f32_e32 v100, v94, v97
	v_mul_f32_e32 v101, v95, v97
	v_exp_f32_e32 v100, v100
	v_exp_f32_e32 v101, v101
	v_add_f32_e32 v98, 1.0, v98
	v_add_f32_e32 v99, 1.0, v99
	v_rcp_f32_e32 v98, v98
	v_rcp_f32_e32 v99, v99
	v_add_f32_e32 v94, 1.0, v100
	v_add_f32_e32 v95, 1.0, v101
	v_rcp_f32_e32 v94, v94
	v_rcp_f32_e32 v95, v95
	v_mul_f32_e32 v96, v96, v96
	v_pk_mul_f32 v[92:93], v[96:97], v[98:99] op_sel_hi:[0,1]
	v_pk_mul_f32 v[88:89], v[88:89], v[92:93]
	v_pk_mul_f32 v[92:93], v[96:97], v[94:95] op_sel_hi:[0,1]
	v_cvt_pk_bf16_f32 v88, v88, v89
	v_mul_f32_e32 v89, v84, v97
	v_pk_mul_f32 v[90:91], v[90:91], v[92:93]
	v_exp_f32_e32 v92, v89
	v_mul_f32_e32 v89, v85, v97
	v_exp_f32_e32 v93, v89
	v_cvt_pk_bf16_f32 v89, v90, v91
	v_add_f32_e32 v90, 1.0, v92
	v_mul_f32_e32 v92, v86, v97
	v_add_f32_e32 v91, 1.0, v93
	v_mul_f32_e32 v93, v87, v97
	v_exp_f32_e32 v92, v92
	v_exp_f32_e32 v93, v93
	v_rcp_f32_e32 v90, v90
	v_rcp_f32_e32 v91, v91
	v_add_f32_e32 v86, 1.0, v92
	v_add_f32_e32 v87, 1.0, v93
	v_rcp_f32_e32 v86, v86
	v_rcp_f32_e32 v87, v87
	v_pk_mul_f32 v[84:85], v[96:97], v[90:91] op_sel_hi:[0,1]
	v_pk_mul_f32 v[80:81], v[80:81], v[84:85]
	v_pk_mul_f32 v[84:85], v[96:97], v[86:87] op_sel_hi:[0,1]
	v_cvt_pk_bf16_f32 v90, v80, v81
	v_fmamk_f32 v80, v190, 0x3a000000, v165
	v_mul_f32_e32 v81, 0x4b800000, v80
	v_cmp_gt_f32_e32 vcc, s45, v80
; __device__ __forceinline__ unsigned cvtpk(float lo, float hi) { f32x2_t v = {lo, hi}; bf16x2_t b = __builtin_convertvector(v, bf16x2_t); return __builtin_bit_cast(unsigned, b); }
;     __device__ __forceinline__ void operator()(const pg8::f32x4 (&acc)[2][2][4][2], const pg8::Unit& u, int wr, int wc, int fr, int fq) const {
;     ...
;         for (int ai = 0; ai < 2; ++ai)
; #pragma unroll
;             for (int m = 0; m < 4; ++m) {
;                 const int row = row0 + ai * 128 + m * 16;
;                 const float rs = rsqrtf(rsv[ai][m] * (1.f / DM) + EPS), c1 = -rs * LOG2E, rs2 = rs * rs;
;                 u32x4 w;
; #pragma unroll
;                 for (int n = 0; n < 2; ++n) {
;                     const pg8::f32x4 g = acc[ai][0][m][n], up = acc[ai][1][m][n];
;                     float o4[4];
; #pragma unroll
;                     for (int k = 0; k < 4; ++k) o4[k] = (g[k] * up[k]) * (rs2 * __builtin_amdgcn_rcpf(1.f + __builtin_amdgcn_exp2f(g[k] * c1)));
;                     w[2 * n] = cvtpk(o4[0], o4[1]); w[2 * n + 1] = cvtpk(o4[2], o4[3]);
;                 }
;                 *(u32x4*)(O + (size_t)row * FF + col0) = w;
	v_pk_mul_f32 v[82:83], v[82:83], v[84:85]
	s_nop 0
	v_cndmask_b32_e32 v80, v80, v81, vcc
	v_cvt_pk_bf16_f32 v91, v82, v83
	v_rsq_f32_e32 v82, v80
	v_mad_i64_i32 v[80:81], s[2:3], v126, s46, v[120:121]
	v_lshl_add_u64 v[80:81], v[80:81], 0, v[122:123]
	global_store_dwordx4 v[80:81], v[88:91], off
	v_mul_f32_e32 v80, 0x45800000, v82
	v_cndmask_b32_e32 v80, v82, v80, vcc
	v_mul_f32_e32 v81, 0xbfb8aa3b, v80
	v_mul_f32_e32 v82, v76, v81
	v_mul_f32_e32 v83, v77, v81
	v_exp_f32_e32 v82, v82
	v_exp_f32_e32 v83, v83
	v_mul_f32_e32 v84, v78, v81
	v_mul_f32_e32 v85, v79, v81
	v_exp_f32_e32 v84, v84
	v_exp_f32_e32 v85, v85
	v_add_f32_e32 v82, 1.0, v82
	v_add_f32_e32 v83, 1.0, v83
	v_rcp_f32_e32 v82, v82
	v_rcp_f32_e32 v83, v83
	v_add_f32_e32 v78, 1.0, v84
	v_add_f32_e32 v79, 1.0, v85
	v_rcp_f32_e32 v78, v78
	v_rcp_f32_e32 v79, v79
	v_mul_f32_e32 v80, v80, v80
	v_pk_mul_f32 v[76:77], v[80:81], v[82:83] op_sel_hi:[0,1]
	v_pk_mul_f32 v[72:73], v[72:73], v[76:77]
	v_pk_mul_f32 v[76:77], v[80:81], v[78:79] op_sel_hi:[0,1]
	v_cvt_pk_bf16_f32 v72, v72, v73
	v_mul_f32_e32 v73, v68, v81
	v_pk_mul_f32 v[74:75], v[74:75], v[76:77]
	v_exp_f32_e32 v76, v73
	v_mul_f32_e32 v73, v69, v81
	v_exp_f32_e32 v77, v73
	v_cvt_pk_bf16_f32 v73, v74, v75
	v_add_f32_e32 v74, 1.0, v76
	v_mul_f32_e32 v76, v70, v81
	v_add_f32_e32 v75, 1.0, v77
	v_mul_f32_e32 v77, v71, v81
	v_exp_f32_e32 v76, v76
	v_exp_f32_e32 v77, v77
	v_rcp_f32_e32 v74, v74
	v_rcp_f32_e32 v75, v75
	v_add_f32_e32 v70, 1.0, v76
	v_add_f32_e32 v71, 1.0, v77
	v_rcp_f32_e32 v70, v70
	v_rcp_f32_e32 v71, v71
	v_pk_mul_f32 v[68:69], v[80:81], v[74:75] op_sel_hi:[0,1]
	v_pk_mul_f32 v[64:65], v[64:65], v[68:69]
	v_pk_mul_f32 v[68:69], v[80:81], v[70:71] op_sel_hi:[0,1]
	v_cvt_pk_bf16_f32 v74, v64, v65
	v_fmamk_f32 v64, v187, 0x3a000000, v165
	v_mul_f32_e32 v65, 0x4b800000, v64
	v_cmp_gt_f32_e32 vcc, s45, v64
	v_pk_mul_f32 v[66:67], v[66:67], v[68:69]
	s_nop 0
	v_cndmask_b32_e32 v64, v64, v65, vcc
	v_cvt_pk_bf16_f32 v75, v66, v67
	v_rsq_f32_e32 v66, v64
	v_mad_i64_i32 v[64:65], s[2:3], v124, s46, v[120:121]
	v_lshl_add_u64 v[64:65], v[64:65], 0, v[122:123]
	global_store_dwordx4 v[64:65], v[72:75], off
	v_mul_f32_e32 v64, 0x45800000, v66
	v_cndmask_b32_e32 v64, v66, v64, vcc
	v_mul_f32_e32 v65, 0xbfb8aa3b, v64
	v_mul_f32_e32 v66, v60, v65
	v_mul_f32_e32 v67, v61, v65
	v_exp_f32_e32 v66, v66
	v_exp_f32_e32 v67, v67
	v_mul_f32_e32 v68, v62, v65
	v_mul_f32_e32 v69, v63, v65
	v_exp_f32_e32 v68, v68
	v_exp_f32_e32 v69, v69
	v_add_f32_e32 v66, 1.0, v66
	v_add_f32_e32 v67, 1.0, v67
	v_rcp_f32_e32 v66, v66
	v_rcp_f32_e32 v67, v67
	v_add_f32_e32 v62, 1.0, v68
	v_add_f32_e32 v63, 1.0, v69
	v_rcp_f32_e32 v62, v62
	v_rcp_f32_e32 v63, v63
	v_mul_f32_e32 v64, v64, v64
	v_pk_mul_f32 v[60:61], v[64:65], v[66:67] op_sel_hi:[0,1]
	v_pk_mul_f32 v[56:57], v[56:57], v[60:61]
	v_pk_mul_f32 v[60:61], v[64:65], v[62:63] op_sel_hi:[0,1]
	v_cvt_pk_bf16_f32 v56, v56, v57
	v_mul_f32_e32 v57, v52, v65
	v_pk_mul_f32 v[58:59], v[58:59], v[60:61]
	v_exp_f32_e32 v60, v57
	v_mul_f32_e32 v57, v53, v65
	v_exp_f32_e32 v61, v57
	v_cvt_pk_bf16_f32 v57, v58, v59
	v_add_f32_e32 v58, 1.0, v60
	v_mul_f32_e32 v60, v54, v65
	v_add_f32_e32 v59, 1.0, v61
	v_mul_f32_e32 v61, v55, v65
	v_exp_f32_e32 v60, v60
	v_exp_f32_e32 v61, v61
	v_rcp_f32_e32 v58, v58
	v_rcp_f32_e32 v59, v59
	v_add_f32_e32 v54, 1.0, v60
	v_add_f32_e32 v55, 1.0, v61
	v_rcp_f32_e32 v54, v54
	v_rcp_f32_e32 v55, v55
	v_pk_mul_f32 v[52:53], v[64:65], v[58:59] op_sel_hi:[0,1]
	v_pk_mul_f32 v[48:49], v[48:49], v[52:53]
	v_pk_mul_f32 v[52:53], v[64:65], v[54:55] op_sel_hi:[0,1]
	v_cvt_pk_bf16_f32 v58, v48, v49
	v_fmamk_f32 v48, v188, 0x3a000000, v165
	v_mul_f32_e32 v49, 0x4b800000, v48
	v_cmp_gt_f32_e32 vcc, s45, v48
	v_pk_mul_f32 v[50:51], v[50:51], v[52:53]
	s_nop 0
	v_cndmask_b32_e32 v48, v48, v49, vcc
	v_cvt_pk_bf16_f32 v59, v50, v51
	v_rsq_f32_e32 v50, v48
	v_mad_i64_i32 v[48:49], s[2:3], v186, s46, v[120:121]
	v_lshl_add_u64 v[48:49], v[48:49], 0, v[122:123]
	global_store_dwordx4 v[48:49], v[56:59], off
	v_mul_f32_e32 v48, 0x45800000, v50
	v_cndmask_b32_e32 v48, v50, v48, vcc
	v_mul_f32_e32 v49, 0xbfb8aa3b, v48
	v_mul_f32_e32 v50, v44, v49
	v_mul_f32_e32 v51, v45, v49
	v_exp_f32_e32 v50, v50
	v_exp_f32_e32 v51, v51
	v_mul_f32_e32 v52, v46, v49
	v_mul_f32_e32 v53, v47, v49
	v_exp_f32_e32 v52, v52
	v_exp_f32_e32 v53, v53
	v_add_f32_e32 v50, 1.0, v50
	v_add_f32_e32 v51, 1.0, v51
	v_rcp_f32_e32 v50, v50
	v_rcp_f32_e32 v51, v51
	v_add_f32_e32 v46, 1.0, v52
	v_add_f32_e32 v47, 1.0, v53
	v_rcp_f32_e32 v46, v46
	v_rcp_f32_e32 v47, v47
	v_mul_f32_e32 v48, v48, v48
	v_pk_mul_f32 v[44:45], v[48:49], v[50:51] op_sel_hi:[0,1]
	v_pk_mul_f32 v[40:41], v[40:41], v[44:45]
	v_pk_mul_f32 v[44:45], v[48:49], v[46:47] op_sel_hi:[0,1]
	v_cvt_pk_bf16_f32 v40, v40, v41
; __device__ __forceinline__ unsigned cvtpk(float lo, float hi) { f32x2_t v = {lo, hi}; bf16x2_t b = __builtin_convertvector(v, bf16x2_t); return __builtin_bit_cast(unsigned, b); }
;     __device__ __forceinline__ void operator()(const pg8::f32x4 (&acc)[2][2][4][2], const pg8::Unit& u, int wr, int wc, int fr, int fq) const {
;     ...
;         for (int ai = 0; ai < 2; ++ai)
; #pragma unroll
;             for (int m = 0; m < 4; ++m) {
;                 const int row = row0 + ai * 128 + m * 16;
;                 const float rs = rsqrtf(rsv[ai][m] * (1.f / DM) + EPS), c1 = -rs * LOG2E, rs2 = rs * rs;
;                 u32x4 w;
; #pragma unroll
;                 for (int n = 0; n < 2; ++n) {
;                     const pg8::f32x4 g = acc[ai][0][m][n], up = acc[ai][1][m][n];
;                     float o4[4];
; #pragma unroll
;                     for (int k = 0; k < 4; ++k) o4[k] = (g[k] * up[k]) * (rs2 * __builtin_amdgcn_rcpf(1.f + __builtin_amdgcn_exp2f(g[k] * c1)));
;                     w[2 * n] = cvtpk(o4[0], o4[1]); w[2 * n + 1] = cvtpk(o4[2], o4[3]);
;                 }
;                 *(u32x4*)(O + (size_t)row * FF + col0) = w;
	v_mul_f32_e32 v41, v36, v49
	v_pk_mul_f32 v[42:43], v[42:43], v[44:45]
	v_exp_f32_e32 v44, v41
	v_mul_f32_e32 v41, v37, v49
	v_exp_f32_e32 v45, v41
	v_cvt_pk_bf16_f32 v41, v42, v43
	v_add_f32_e32 v42, 1.0, v44
	v_mul_f32_e32 v44, v38, v49
	v_add_f32_e32 v43, 1.0, v45
	v_mul_f32_e32 v45, v39, v49
	v_exp_f32_e32 v44, v44
	v_exp_f32_e32 v45, v45
	v_rcp_f32_e32 v42, v42
	v_rcp_f32_e32 v43, v43
	v_add_f32_e32 v38, 1.0, v44
	v_add_f32_e32 v39, 1.0, v45
	v_rcp_f32_e32 v38, v38
	v_rcp_f32_e32 v39, v39
	v_pk_mul_f32 v[36:37], v[48:49], v[42:43] op_sel_hi:[0,1]
	v_pk_mul_f32 v[32:33], v[32:33], v[36:37]
	v_pk_mul_f32 v[36:37], v[48:49], v[38:39] op_sel_hi:[0,1]
	v_cvt_pk_bf16_f32 v42, v32, v33
	v_fmamk_f32 v32, v127, 0x3a000000, v165
	v_mul_f32_e32 v33, 0x4b800000, v32
	v_cmp_gt_f32_e32 vcc, s45, v32
	v_pk_mul_f32 v[34:35], v[34:35], v[36:37]
	s_nop 0
	v_cndmask_b32_e32 v32, v32, v33, vcc
	v_cvt_pk_bf16_f32 v43, v34, v35
	v_rsq_f32_e32 v34, v32
	v_mad_i64_i32 v[32:33], s[2:3], v167, s46, v[120:121]
	v_lshl_add_u64 v[32:33], v[32:33], 0, v[122:123]
	global_store_dwordx4 v[32:33], v[40:43], off
	v_mul_f32_e32 v32, 0x45800000, v34
	v_cndmask_b32_e32 v32, v34, v32, vcc
	v_mul_f32_e32 v33, 0xbfb8aa3b, v32
	v_mul_f32_e32 v34, v28, v33
	v_mul_f32_e32 v35, v29, v33
	v_exp_f32_e32 v34, v34
	v_exp_f32_e32 v35, v35
	v_mul_f32_e32 v36, v30, v33
	v_mul_f32_e32 v37, v31, v33
	v_exp_f32_e32 v36, v36
	v_exp_f32_e32 v37, v37
	v_add_f32_e32 v34, 1.0, v34
	v_add_f32_e32 v35, 1.0, v35
	v_rcp_f32_e32 v34, v34
	v_rcp_f32_e32 v35, v35
	v_add_f32_e32 v30, 1.0, v36
	v_add_f32_e32 v31, 1.0, v37
	v_rcp_f32_e32 v30, v30
	v_rcp_f32_e32 v31, v31
	v_mul_f32_e32 v32, v32, v32
	v_pk_mul_f32 v[28:29], v[32:33], v[34:35] op_sel_hi:[0,1]
	v_pk_mul_f32 v[24:25], v[24:25], v[28:29]
	v_pk_mul_f32 v[28:29], v[32:33], v[30:31] op_sel_hi:[0,1]
	v_cvt_pk_bf16_f32 v24, v24, v25
	v_mul_f32_e32 v25, v20, v33
	v_pk_mul_f32 v[26:27], v[26:27], v[28:29]
	v_exp_f32_e32 v28, v25
	v_mul_f32_e32 v25, v21, v33
	v_exp_f32_e32 v29, v25
	v_cvt_pk_bf16_f32 v25, v26, v27
	v_add_f32_e32 v26, 1.0, v28
	v_mul_f32_e32 v28, v22, v33
	v_add_f32_e32 v27, 1.0, v29
	v_mul_f32_e32 v29, v23, v33
	v_exp_f32_e32 v28, v28
	v_exp_f32_e32 v29, v29
	v_rcp_f32_e32 v26, v26
	v_rcp_f32_e32 v27, v27
	v_add_f32_e32 v22, 1.0, v28
	v_add_f32_e32 v23, 1.0, v29
	v_rcp_f32_e32 v22, v22
	v_rcp_f32_e32 v23, v23
	v_pk_mul_f32 v[20:21], v[32:33], v[26:27] op_sel_hi:[0,1]
	v_pk_mul_f32 v[16:17], v[16:17], v[20:21]
	v_pk_mul_f32 v[20:21], v[32:33], v[22:23] op_sel_hi:[0,1]
	v_cvt_pk_bf16_f32 v26, v16, v17
	v_fmamk_f32 v16, v125, 0x3a000000, v165
	v_mul_f32_e32 v17, 0x4b800000, v16
	v_cmp_gt_f32_e32 vcc, s45, v16
	v_pk_mul_f32 v[18:19], v[18:19], v[20:21]
	s_nop 0
	v_cndmask_b32_e32 v16, v16, v17, vcc
	v_cvt_pk_bf16_f32 v27, v18, v19
	v_rsq_f32_e32 v18, v16
	v_mad_i64_i32 v[16:17], s[2:3], v166, s46, v[120:121]
	v_lshl_add_u64 v[16:17], v[16:17], 0, v[122:123]
	global_store_dwordx4 v[16:17], v[24:27], off
	v_mul_f32_e32 v16, 0x45800000, v18
	v_cndmask_b32_e32 v16, v18, v16, vcc
	v_mul_f32_e32 v17, 0xbfb8aa3b, v16
	v_mul_f32_e32 v18, v12, v17
	v_mul_f32_e32 v19, v13, v17
	v_exp_f32_e32 v18, v18
	v_exp_f32_e32 v19, v19
	v_mul_f32_e32 v20, v14, v17
	v_mul_f32_e32 v21, v15, v17
	v_exp_f32_e32 v20, v20
	v_exp_f32_e32 v21, v21
	v_add_f32_e32 v18, 1.0, v18
	v_add_f32_e32 v19, 1.0, v19
	v_rcp_f32_e32 v18, v18
	v_rcp_f32_e32 v19, v19
	v_add_f32_e32 v14, 1.0, v20
	v_add_f32_e32 v15, 1.0, v21
	v_rcp_f32_e32 v14, v14
	v_rcp_f32_e32 v15, v15
	v_mul_f32_e32 v16, v16, v16
	v_pk_mul_f32 v[12:13], v[16:17], v[18:19] op_sel_hi:[0,1]
	v_pk_mul_f32 v[8:9], v[8:9], v[12:13]
	v_pk_mul_f32 v[12:13], v[16:17], v[14:15] op_sel_hi:[0,1]
	v_cvt_pk_bf16_f32 v8, v8, v9
	v_mul_f32_e32 v9, v4, v17
	v_pk_mul_f32 v[10:11], v[10:11], v[12:13]
	v_exp_f32_e32 v12, v9
	v_mul_f32_e32 v9, v5, v17
	v_exp_f32_e32 v13, v9
	v_cvt_pk_bf16_f32 v9, v10, v11
	v_add_f32_e32 v10, 1.0, v12
	v_mul_f32_e32 v12, v6, v17
	v_add_f32_e32 v11, 1.0, v13
	v_mul_f32_e32 v13, v7, v17
	v_exp_f32_e32 v12, v12
	v_exp_f32_e32 v13, v13
	v_rcp_f32_e32 v10, v10
	v_rcp_f32_e32 v11, v11
	v_add_f32_e32 v6, 1.0, v12
	v_add_f32_e32 v7, 1.0, v13
	v_rcp_f32_e32 v6, v6
	v_rcp_f32_e32 v7, v7
	v_pk_mul_f32 v[4:5], v[16:17], v[10:11] op_sel_hi:[0,1]
	v_pk_mul_f32 v[0:1], v[0:1], v[4:5]
	s_andn2_b64 vcc, exec, s[0:1]
	v_pk_mul_f32 v[4:5], v[16:17], v[6:7] op_sel_hi:[0,1]
	v_pk_mul_f32 v[2:3], v[2:3], v[4:5]
	v_cvt_pk_bf16_f32 v10, v0, v1
	v_mad_i64_i32 v[0:1], s[2:3], v145, s46, v[120:121]
	v_cvt_pk_bf16_f32 v11, v2, v3
	v_lshl_add_u64 v[0:1], v[0:1], 0, v[122:123]
	s_mov_b64 s[0:1], -1
	global_store_dwordx4 v[0:1], v[8:11], off
	s_cbranch_vccnz .LBB0_1072
	s_andn2_b64 vcc, exec, s[4:5]
	s_cbranch_vccnz .LBB0_1071
	s_barrier
	s_branch .LBB0_1071
